# G2 epilogue g tiles: the 16 QV read-modify-write loads prefetched through a 4-row-group register ring with counted waits instead of 16 serialized vmcnt(0) round trips (plus conv2d edit)
# speedup vs baseline: 1.0216x; 1.0036x over previous
; #define LAS __attribute__((address_space(3)))
;     template <int NA, int NM> __device__ __forceinline__ void operator()(const f32x4 (&acc)[NA][2][NM][2], const pg8::Unit& u, int ro, int wr, int wc, int fr, int fq) const {
;         const int j = u.pm < 32 ? 0 : (u.pm < 64 ? 1 : 2);
;         const int colt = 4096 + u.pn * 256 + wc * 32 + 8 * fq;
;         const LAS float* rsl = EpiCommon::rstd_slot(ssq, u, wr, wc, fr, fq);
;         f32x4 bv[2][2];
; #pragma unroll
;         for (int bj = 0; bj < 2; ++bj)
; #pragma unroll
;             for (int n = 0; n < 2; ++n) bv[bj][n] = *(const f32x4*)(bias + (size_t)j * PIN + colt + bj * 128 + 4 * n);
; #pragma unroll
;         for (int ai = 0; ai < NA; ++ai)
; #pragma unroll
;             for (int m = 0; m < NM; ++m) {
;                 const int row = u.pm * 256 + ro + ai * 128 + wr * 64 + m * 16 + fr;
;                 const float rs = rsl[ro + ai * 128 + m * 16];
;                 f32x4 v[2][2];
; #pragma unroll
;                 for (int bj = 0; bj < 2; ++bj) { v[bj][0] = acc[ai][bj][m][0] * rs + bv[bj][0]; v[bj][1] = acc[ai][bj][m][1] * rs + bv[bj][1]; }
;                 if (u.pn < 4) {
; #pragma unroll
;                     for (int bj = 0; bj < 2; ++bj) {
;                         bf16_t* p = QV + (size_t)row * 2048 + (colt - 4096) + bj * 128;
;                         const u32x4 on = *(const u32x4*)p;
;                         u32x4 w;
;                         w.x = pk2(bflo(on.x) * siluf_(v[bj][0].x), bfhi(on.x) * siluf_(v[bj][0].y)); w.y = pk2(bflo(on.y) * siluf_(v[bj][0].z), bfhi(on.y) * siluf_(v[bj][0].w));
;                         w.z = pk2(bflo(on.z) * siluf_(v[bj][1].x), bfhi(on.z) * siluf_(v[bj][1].y)); w.w = pk2(bflo(on.w) * siluf_(v[bj][1].z), bfhi(on.w) * siluf_(v[bj][1].w));
;                         if (!dry) *(u32x4*)p = w; else asm volatile("" :: "v"(w));
;                     }
;                 } else if (u.pn < 12) {
;                     const int t = u.pn - 4;
;                     const f32x4 a0 = v[0][0], a1 = v[0][1], b0 = v[1][0], b1 = v[1][1];
;                     u32x4 w;
;                     w.x = pk2(a0.x * sigmoidf_(b0.x), a0.y * sigmoidf_(b0.y)); w.y = pk2(a0.z * sigmoidf_(b0.z), a0.w * sigmoidf_(b0.w));
;                     w.z = pk2(a1.x * sigmoidf_(b1.x), a1.y * sigmoidf_(b1.y)); w.w = pk2(a1.z * sigmoidf_(b1.z), a1.w * sigmoidf_(b1.w));
.LBB0_948:
	s_cmp_lt_i32 s64, 64
	s_movk_i32 s0, 0x2400
	s_cselect_b32 s0, s0, 0x4800
	s_lshl_b32 s28, s70, 8
	s_lshl_b32 s1, s8, 10
	s_cmp_gt_i32 s64, 31
	s_cselect_b32 s0, s0, 0
	s_lshl_b32 s0, s0, 2
	v_readlane_b32 s8, v255, 41
	v_add_u32_e32 v170, s28, v180
	v_readlane_b32 s9, v255, 42
	s_add_u32 s8, s8, s0
	s_addc_u32 s9, s9, 0
	v_ashrrev_i32_e32 v171, 31, v170
	v_lshl_add_u64 v[26:27], v[170:171], 2, s[8:9]
	global_load_dwordx4 v[22:25], v[26:27], off offset:16
	global_load_dwordx4 v[30:33], v[26:27], off
	global_load_dwordx4 v[18:21], v[26:27], off offset:528
	s_nop 0
	global_load_dwordx4 v[26:29], v[26:27], off offset:512
	v_add_u32_e32 v190, s1, v188
	ds_read_b32 v0, v190
	s_lshl_b32 s7, s64, 8
	s_cmp_gt_i32 s70, 3
	s_cselect_b64 s[72:73], -1, 0
	v_readlane_b32 s36, v252, 63
	s_mov_b64 s[30:31], -1
	s_and_b64 vcc, exec, s[72:73]
	v_readlane_b32 s37, v253, 0
	v_readlane_b32 s40, v253, 3
	v_readlane_b32 s41, v253, 4
	v_readlane_b32 s42, v253, 5
	v_readlane_b32 s43, v253, 6
	v_readlane_b32 s44, v253, 7
	v_readlane_b32 s45, v253, 8
	v_readlane_b32 s46, v253, 9
	v_readlane_b32 s47, v253, 10
	v_readlane_b32 s48, v253, 11
	v_readlane_b32 s49, v253, 12
	v_readlane_b32 s50, v253, 13
	v_readlane_b32 s51, v253, 14
	v_readlane_b32 s38, v253, 1
	v_readlane_b32 s39, v253, 2
	s_cmp_gt_i32 s70, 3
	s_cbranch_scc1 .Lg2pf_skip
	v_readlane_b32 s100, v254, 19
	v_readlane_b32 s101, v254, 20
	v_add_u32_e32 v244, s7, v147
	v_ashrrev_i32_e32 v245, 31, v244
	v_lshlrev_b64 v[244:245], 12, v[244:245]
	s_nop 1
	v_lshl_add_u64 v[244:245], s[100:101], 0, v[244:245]
	v_lshl_add_u64 v[244:245], v[170:171], 1, v[244:245]
	s_mov_b32 s100, 0xffffe000
	s_mov_b32 s101, -1
	v_lshl_add_u64 v[244:245], v[244:245], 0, s[100:101]
	global_load_dwordx4 v[210:213], v[244:245], off
	global_load_dwordx4 v[214:217], v[244:245], off offset:256
	s_mov_b32 s100, 0x10000
	s_mov_b32 s101, 0
	v_lshl_add_u64 v[246:247], v[244:245], 0, s[100:101]
	global_load_dwordx4 v[218:221], v[246:247], off
	global_load_dwordx4 v[222:225], v[246:247], off offset:256
	v_lshl_add_u64 v[246:247], v[246:247], 0, s[100:101]
	global_load_dwordx4 v[226:229], v[246:247], off
	global_load_dwordx4 v[230:233], v[246:247], off offset:256
	v_lshl_add_u64 v[246:247], v[246:247], 0, s[100:101]
	global_load_dwordx4 v[234:237], v[246:247], off
	global_load_dwordx4 v[240:243], v[246:247], off offset:256
	s_waitcnt vmcnt(8) lgkmcnt(0)
	s_branch .Lg2pf_join
.Lg2pf_skip:
	s_waitcnt vmcnt(0) lgkmcnt(0)
.Lg2pf_join:
	v_pk_fma_f32 v[172:173], v[138:139], v[0:1], v[22:23] op_sel_hi:[1,0,1]
	v_pk_fma_f32 v[174:175], v[144:145], v[0:1], v[32:33] op_sel_hi:[1,0,1]
	v_pk_fma_f32 v[176:177], v[142:143], v[0:1], v[30:31] op_sel_hi:[1,0,1]
	v_pk_fma_f32 v[142:143], v[140:141], v[0:1], v[24:25] op_sel_hi:[1,0,1]
	v_pk_fma_f32 v[138:139], v[136:137], v[0:1], v[28:29] op_sel_hi:[1,0,1]
	v_pk_fma_f32 v[140:141], v[134:135], v[0:1], v[26:27] op_sel_hi:[1,0,1]
	v_pk_fma_f32 v[134:135], v[132:133], v[0:1], v[20:21] op_sel_hi:[1,0,1]
	v_pk_fma_f32 v[136:137], v[130:131], v[0:1], v[18:19] op_sel_hi:[1,0,1]
	v_add_u32_e32 v130, s7, v147
	s_cbranch_vccz .LBB0_954
	s_cmp_gt_u32 s70, 11
	s_cbranch_scc0 .LBB0_951
	v_readlane_b32 s0, v251, 12
	s_cmp_lt_u32 s70, 16
	v_readlane_b32 s1, v251, 13
	s_cselect_b32 s9, s23, s1
	s_cselect_b32 s8, s22, s0
	v_ashrrev_i32_e32 v131, 31, v130
	s_and_b32 s0, s28, 0x300
	v_lshlrev_b64 v[132:133], 11, v[130:131]
	v_or_b32_e32 v0, s0, v179
	v_lshl_add_u64 v[132:133], s[8:9], 0, v[132:133]
	v_lshlrev_b32_e32 v0, 1, v0
	v_lshl_add_u64 v[132:133], v[132:133], 0, v[0:1]
	v_mul_f32_e32 v0, 0xbfb8aa3b, v176
	v_mul_f32_e32 v131, 0xbfb8aa3b, v177
	v_exp_f32_e32 v0, v0
	v_exp_f32_e32 v131, v131
	s_mov_b64 s[30:31], 0
	v_add_f32_e32 v0, 1.0, v0
	v_add_f32_e32 v131, 1.0, v131
	v_rcp_f32_e32 v0, v0
	v_rcp_f32_e32 v131, v131
	s_nop 0
	v_cvt_pk_bf16_f32 v192, v0, v131
	v_mul_f32_e32 v0, 0xbfb8aa3b, v174
	v_mul_f32_e32 v131, 0xbfb8aa3b, v175
	v_exp_f32_e32 v0, v0
	v_exp_f32_e32 v131, v131
	v_add_f32_e32 v0, 1.0, v0
	v_add_f32_e32 v131, 1.0, v131
	v_rcp_f32_e32 v0, v0
	v_rcp_f32_e32 v131, v131
	s_nop 0
	v_cvt_pk_bf16_f32 v193, v0, v131
	v_mul_f32_e32 v0, 0xbfb8aa3b, v172
	v_mul_f32_e32 v131, 0xbfb8aa3b, v173
	v_exp_f32_e32 v0, v0
	v_exp_f32_e32 v131, v131
	v_add_f32_e32 v0, 1.0, v0
	v_add_f32_e32 v131, 1.0, v131
	v_rcp_f32_e32 v0, v0
	v_rcp_f32_e32 v131, v131
	s_nop 0
	v_cvt_pk_bf16_f32 v194, v0, v131
	v_mul_f32_e32 v0, 0xbfb8aa3b, v142
	v_mul_f32_e32 v131, 0xbfb8aa3b, v143
	v_exp_f32_e32 v0, v0
	v_exp_f32_e32 v131, v131
	v_add_f32_e32 v0, 1.0, v0
	v_add_f32_e32 v131, 1.0, v131
	v_rcp_f32_e32 v0, v0
	v_rcp_f32_e32 v131, v131
	s_nop 0
	v_cvt_pk_bf16_f32 v195, v0, v131
	v_mul_f32_e32 v0, 0xbfb8aa3b, v140
	v_mul_f32_e32 v131, 0xbfb8aa3b, v141
	v_exp_f32_e32 v0, v0
	v_exp_f32_e32 v131, v131
	global_store_dwordx4 v[132:133], v[192:195], off
	v_add_f32_e32 v0, 1.0, v0
	v_add_f32_e32 v131, 1.0, v131
	v_rcp_f32_e32 v0, v0
	v_rcp_f32_e32 v131, v131
	s_nop 0
	v_cvt_pk_bf16_f32 v192, v0, v131
	v_mul_f32_e32 v0, 0xbfb8aa3b, v138
	v_mul_f32_e32 v131, 0xbfb8aa3b, v139
	v_exp_f32_e32 v0, v0
	v_exp_f32_e32 v131, v131
	v_add_f32_e32 v0, 1.0, v0
	v_add_f32_e32 v131, 1.0, v131
	v_rcp_f32_e32 v0, v0
	v_rcp_f32_e32 v131, v131
	s_nop 0
	v_cvt_pk_bf16_f32 v193, v0, v131
	v_mul_f32_e32 v0, 0xbfb8aa3b, v136
	v_mul_f32_e32 v131, 0xbfb8aa3b, v137
	v_exp_f32_e32 v0, v0
	v_exp_f32_e32 v131, v131
	v_add_f32_e32 v0, 1.0, v0
	v_add_f32_e32 v131, 1.0, v131
	v_rcp_f32_e32 v0, v0
	v_rcp_f32_e32 v131, v131
	s_nop 0
	v_cvt_pk_bf16_f32 v194, v0, v131
	v_mul_f32_e32 v0, 0xbfb8aa3b, v134
	v_mul_f32_e32 v131, 0xbfb8aa3b, v135
	v_exp_f32_e32 v0, v0
	v_exp_f32_e32 v131, v131
	v_add_f32_e32 v0, 1.0, v0
	v_add_f32_e32 v131, 1.0, v131
	v_rcp_f32_e32 v0, v0
	v_rcp_f32_e32 v131, v131
	s_nop 0
	v_cvt_pk_bf16_f32 v195, v0, v131
	global_store_dwordx4 v[132:133], v[192:195], off offset:256

; __device__ __forceinline__ unsigned pk2(float lo, float hi) { const f32x2 v = {lo, hi}; const bf16x2_t b = __builtin_convertvector(v, bf16x2_t); return __builtin_bit_cast(unsigned, b); }
; __device__ __forceinline__ float siluf_(float x) { return x * sigmoidf_(x); }
;     template <int NA, int NM> __device__ __forceinline__ void operator()(const f32x4 (&acc)[NA][2][NM][2], const pg8::Unit& u, int ro, int wr, int wc, int fr, int fq) const {
;     ...
;                     for (int bj = 0; bj < 2; ++bj) {
;                         bf16_t* p = QV + (size_t)row * 2048 + (colt - 4096) + bj * 128;
;                         const u32x4 on = *(const u32x4*)p;
;                         u32x4 w;
;                         w.x = pk2(bflo(on.x) * siluf_(v[bj][0].x), bfhi(on.x) * siluf_(v[bj][0].y)); w.y = pk2(bflo(on.y) * siluf_(v[bj][0].z), bfhi(on.y) * siluf_(v[bj][0].w));
;                         w.z = pk2(bflo(on.z) * siluf_(v[bj][1].x), bfhi(on.z) * siluf_(v[bj][1].y)); w.w = pk2(bflo(on.w) * siluf_(v[bj][1].z), bfhi(on.w) * siluf_(v[bj][1].w));
;                         if (!dry) *(u32x4*)p = w; else asm volatile("" :: "v"(w));
.LBB0_954:
	s_andn2_b64 vcc, exec, s[30:31]
	s_cbranch_vccnz .LBB0_963
	v_ashrrev_i32_e32 v131, 31, v130
	v_readlane_b32 s0, v254, 19
	v_lshlrev_b64 v[130:131], 12, v[130:131]
	v_readlane_b32 s1, v254, 20
	v_mul_f32_e32 v0, 0xbfb8aa3b, v176
	v_exp_f32_e32 v0, v0
	v_lshl_add_u64 v[130:131], s[0:1], 0, v[130:131]
	v_lshl_add_u64 v[144:145], v[170:171], 1, v[130:131]
	v_add_co_u32_e32 v130, vcc, 0xffffe000, v144
	v_add_f32_e32 v0, 1.0, v0
	s_nop 0
	v_addc_co_u32_e32 v131, vcc, -1, v145, vcc
	v_rcp_f32_e32 v162, v0
	v_mul_f32_e32 v0, 0xbfb8aa3b, v177
	v_exp_f32_e32 v0, v0
	s_mov_b64 s[30:31], -1
	s_and_b64 vcc, exec, s[2:3]
	v_add_f32_e32 v0, 1.0, v0
	v_rcp_f32_e32 v163, v0
	v_mul_f32_e32 v0, 0xbfb8aa3b, v174
	v_exp_f32_e32 v0, v0
	v_pk_mul_f32 v[162:163], v[176:177], v[162:163]
	v_add_f32_e32 v0, 1.0, v0
	s_waitcnt vmcnt(7)
	v_lshlrev_b32_e32 v164, 16, v210
	v_and_b32_e32 v165, 0xffff0000, v210
	v_pk_mul_f32 v[162:163], v[162:163], v[164:165]
	v_lshlrev_b32_e32 v164, 16, v211
	v_cvt_pk_bf16_f32 v130, v162, v163
	v_rcp_f32_e32 v162, v0
	v_mul_f32_e32 v0, 0xbfb8aa3b, v175
	v_exp_f32_e32 v0, v0
	v_and_b32_e32 v165, 0xffff0000, v211
	v_add_f32_e32 v0, 1.0, v0
	v_rcp_f32_e32 v163, v0
	v_mul_f32_e32 v0, 0xbfb8aa3b, v172
	v_exp_f32_e32 v0, v0
	v_pk_mul_f32 v[162:163], v[174:175], v[162:163]
	s_nop 0
	v_pk_mul_f32 v[162:163], v[162:163], v[164:165]
	v_add_f32_e32 v0, 1.0, v0
	v_cvt_pk_bf16_f32 v131, v162, v163
	v_rcp_f32_e32 v162, v0
	v_mul_f32_e32 v0, 0xbfb8aa3b, v173
	v_exp_f32_e32 v0, v0
	v_lshlrev_b32_e32 v164, 16, v212
	v_and_b32_e32 v165, 0xffff0000, v212
	v_add_f32_e32 v0, 1.0, v0
	v_rcp_f32_e32 v163, v0
	v_mul_f32_e32 v0, 0xbfb8aa3b, v142
	v_exp_f32_e32 v0, v0
	v_pk_mul_f32 v[162:163], v[172:173], v[162:163]
	s_nop 0
	v_pk_mul_f32 v[162:163], v[162:163], v[164:165]
	v_add_f32_e32 v0, 1.0, v0
	v_cvt_pk_bf16_f32 v132, v162, v163
	v_rcp_f32_e32 v162, v0
	v_mul_f32_e32 v0, 0xbfb8aa3b, v143
	v_exp_f32_e32 v0, v0
	v_lshlrev_b32_e32 v164, 16, v213
	v_and_b32_e32 v165, 0xffff0000, v213
	v_add_f32_e32 v0, 1.0, v0
	v_rcp_f32_e32 v163, v0
	s_nop 0
	v_pk_mul_f32 v[142:143], v[142:143], v[162:163]
	s_nop 0
	v_pk_mul_f32 v[142:143], v[142:143], v[164:165]
	s_nop 0
	v_cvt_pk_bf16_f32 v133, v142, v143
	s_cbranch_vccz .LBB0_957
	s_mov_b64 s[30:31], 0

; __device__ __forceinline__ unsigned pk2(float lo, float hi) { const f32x2 v = {lo, hi}; const bf16x2_t b = __builtin_convertvector(v, bf16x2_t); return __builtin_bit_cast(unsigned, b); }
; __device__ __forceinline__ float siluf_(float x) { return x * sigmoidf_(x); }
;     template <int NA, int NM> __device__ __forceinline__ void operator()(const f32x4 (&acc)[NA][2][NM][2], const pg8::Unit& u, int ro, int wr, int wc, int fr, int fq) const {
;     ...
;                     for (int bj = 0; bj < 2; ++bj) {
;                         bf16_t* p = QV + (size_t)row * 2048 + (colt - 4096) + bj * 128;
;                         const u32x4 on = *(const u32x4*)p;
;                         u32x4 w;
;                         w.x = pk2(bflo(on.x) * siluf_(v[bj][0].x), bfhi(on.x) * siluf_(v[bj][0].y)); w.y = pk2(bflo(on.y) * siluf_(v[bj][0].z), bfhi(on.y) * siluf_(v[bj][0].w));
;                         w.z = pk2(bflo(on.z) * siluf_(v[bj][1].x), bfhi(on.z) * siluf_(v[bj][1].y)); w.w = pk2(bflo(on.w) * siluf_(v[bj][1].z), bfhi(on.w) * siluf_(v[bj][1].w));
;                         if (!dry) *(u32x4*)p = w; else asm volatile("" :: "v"(w));
.LBB0_959:
	s_nop 1
	v_add_co_u32_e32 v130, vcc, 0xfffff000, v144
	v_mul_f32_e32 v0, 0xbfb8aa3b, v140
	s_nop 0
	v_addc_co_u32_e32 v131, vcc, -1, v145, vcc
	v_exp_f32_e32 v0, v0
	s_mov_b64 s[30:31], -1
	s_and_b64 vcc, exec, s[2:3]
	v_add_f32_e32 v0, 1.0, v0
	v_rcp_f32_e32 v142, v0
	v_mul_f32_e32 v0, 0xbfb8aa3b, v141
	v_exp_f32_e32 v0, v0
	s_waitcnt vmcnt(6)
	v_lshlrev_b32_e32 v162, 16, v214
	v_add_f32_e32 v0, 1.0, v0
	v_rcp_f32_e32 v143, v0
	v_mul_f32_e32 v0, 0xbfb8aa3b, v138
	v_exp_f32_e32 v0, v0
	v_and_b32_e32 v163, 0xffff0000, v214
	v_pk_mul_f32 v[140:141], v[140:141], v[142:143]
	v_lshlrev_b32_e32 v142, 16, v215
	v_pk_mul_f32 v[140:141], v[140:141], v[162:163]
	v_add_f32_e32 v0, 1.0, v0
	v_cvt_pk_bf16_f32 v130, v140, v141
	v_rcp_f32_e32 v140, v0
	v_mul_f32_e32 v0, 0xbfb8aa3b, v139
	v_exp_f32_e32 v0, v0
	v_and_b32_e32 v143, 0xffff0000, v215
	v_add_f32_e32 v0, 1.0, v0
	v_rcp_f32_e32 v141, v0
	v_mul_f32_e32 v0, 0xbfb8aa3b, v136
	v_exp_f32_e32 v0, v0
	v_pk_mul_f32 v[138:139], v[138:139], v[140:141]
	s_nop 0
	v_pk_mul_f32 v[138:139], v[138:139], v[142:143]
	v_add_f32_e32 v0, 1.0, v0
	v_cvt_pk_bf16_f32 v131, v138, v139
	v_rcp_f32_e32 v138, v0
	v_mul_f32_e32 v0, 0xbfb8aa3b, v137
	v_exp_f32_e32 v0, v0
	v_lshlrev_b32_e32 v140, 16, v216
	v_and_b32_e32 v141, 0xffff0000, v216
	v_add_f32_e32 v0, 1.0, v0
	v_rcp_f32_e32 v139, v0
	v_mul_f32_e32 v0, 0xbfb8aa3b, v134
	v_exp_f32_e32 v0, v0
	v_pk_mul_f32 v[136:137], v[136:137], v[138:139]
	s_nop 0
	v_pk_mul_f32 v[136:137], v[136:137], v[140:141]
	v_add_f32_e32 v0, 1.0, v0
	v_cvt_pk_bf16_f32 v132, v136, v137
	v_rcp_f32_e32 v136, v0
	v_mul_f32_e32 v0, 0xbfb8aa3b, v135
	v_exp_f32_e32 v0, v0
	v_lshlrev_b32_e32 v138, 16, v217
	v_and_b32_e32 v139, 0xffff0000, v217
	v_add_f32_e32 v0, 1.0, v0
	v_rcp_f32_e32 v137, v0
	s_nop 0
	v_pk_mul_f32 v[134:135], v[134:135], v[136:137]
	s_nop 0
	v_pk_mul_f32 v[134:135], v[134:135], v[138:139]
	s_nop 0
	v_cvt_pk_bf16_f32 v133, v134, v135
	s_cbranch_vccz .LBB0_961
	s_mov_b64 s[30:31], 0
.LBB0_961:
	s_mov_b32 s100, 0x80000
	s_mov_b32 s101, 0
	v_lshl_add_u64 v[246:247], v[244:245], 0, s[100:101]
	global_load_dwordx4 v[210:213], v[246:247], off
	global_load_dwordx4 v[214:217], v[246:247], off offset:256
	s_andn2_b64 vcc, exec, s[30:31]
	s_cbranch_vccnz .LBB0_963
	s_movk_i32 s0, 0xe100
	s_mov_b32 s1, -1
	v_lshl_add_u64 v[134:135], v[144:145], 0, s[0:1]
	global_store_dwordx4 v[134:135], v[130:133], off

; __device__ __forceinline__ unsigned pk2(float lo, float hi) { const f32x2 v = {lo, hi}; const bf16x2_t b = __builtin_convertvector(v, bf16x2_t); return __builtin_bit_cast(unsigned, b); }
; __device__ __forceinline__ float siluf_(float x) { return x * sigmoidf_(x); }
;     template <int NA, int NM> __device__ __forceinline__ void operator()(const f32x4 (&acc)[NA][2][NM][2], const pg8::Unit& u, int ro, int wr, int wc, int fr, int fq) const {
;     ...
;                     for (int bj = 0; bj < 2; ++bj) {
;                         bf16_t* p = QV + (size_t)row * 2048 + (colt - 4096) + bj * 128;
;                         const u32x4 on = *(const u32x4*)p;
;                         u32x4 w;
;                         w.x = pk2(bflo(on.x) * siluf_(v[bj][0].x), bfhi(on.x) * siluf_(v[bj][0].y)); w.y = pk2(bflo(on.y) * siluf_(v[bj][0].z), bfhi(on.y) * siluf_(v[bj][0].w));
;                         w.z = pk2(bflo(on.z) * siluf_(v[bj][1].x), bfhi(on.z) * siluf_(v[bj][1].y)); w.w = pk2(bflo(on.w) * siluf_(v[bj][1].z), bfhi(on.w) * siluf_(v[bj][1].w));
;                         if (!dry) *(u32x4*)p = w; else asm volatile("" :: "v"(w));
.LBB0_969:
	s_andn2_b64 vcc, exec, s[30:31]
	s_cbranch_vccnz .LBB0_978
	v_ashrrev_i32_e32 v115, 31, v114
	v_readlane_b32 s0, v254, 19
	v_lshlrev_b64 v[114:115], 12, v[114:115]
	v_readlane_b32 s1, v254, 20
	v_mul_f32_e32 v0, 0xbfb8aa3b, v134
	v_exp_f32_e32 v0, v0
	v_lshl_add_u64 v[114:115], s[0:1], 0, v[114:115]
	v_lshl_add_u64 v[126:127], v[170:171], 1, v[114:115]
	v_add_co_u32_e32 v114, vcc, 0xffffe000, v126
	v_add_f32_e32 v0, 1.0, v0
	s_nop 0
	v_addc_co_u32_e32 v115, vcc, -1, v127, vcc
	v_rcp_f32_e32 v136, v0
	v_mul_f32_e32 v0, 0xbfb8aa3b, v135
	v_exp_f32_e32 v0, v0
	s_mov_b64 s[30:31], -1
	s_and_b64 vcc, exec, s[2:3]
	v_add_f32_e32 v0, 1.0, v0
	v_rcp_f32_e32 v137, v0
	v_mul_f32_e32 v0, 0xbfb8aa3b, v132
	v_exp_f32_e32 v0, v0
	v_pk_mul_f32 v[134:135], v[134:135], v[136:137]
	v_add_f32_e32 v0, 1.0, v0
	s_waitcnt vmcnt(7)
	v_lshlrev_b32_e32 v138, 16, v218
	v_and_b32_e32 v139, 0xffff0000, v218
	v_pk_mul_f32 v[134:135], v[134:135], v[138:139]
	v_lshlrev_b32_e32 v136, 16, v219
	v_cvt_pk_bf16_f32 v114, v134, v135
	v_rcp_f32_e32 v134, v0
	v_mul_f32_e32 v0, 0xbfb8aa3b, v133
	v_exp_f32_e32 v0, v0
	v_and_b32_e32 v137, 0xffff0000, v219
	v_add_f32_e32 v0, 1.0, v0
	v_rcp_f32_e32 v135, v0
	v_mul_f32_e32 v0, 0xbfb8aa3b, v130
	v_exp_f32_e32 v0, v0
	v_pk_mul_f32 v[132:133], v[132:133], v[134:135]
	s_nop 0
	v_pk_mul_f32 v[132:133], v[132:133], v[136:137]
	v_add_f32_e32 v0, 1.0, v0
	v_cvt_pk_bf16_f32 v115, v132, v133
	v_rcp_f32_e32 v132, v0
	v_mul_f32_e32 v0, 0xbfb8aa3b, v131
	v_exp_f32_e32 v0, v0
	v_lshlrev_b32_e32 v134, 16, v220
	v_and_b32_e32 v135, 0xffff0000, v220
	v_add_f32_e32 v0, 1.0, v0
	v_rcp_f32_e32 v133, v0
	v_mul_f32_e32 v0, 0xbfb8aa3b, v128
	v_exp_f32_e32 v0, v0
	v_pk_mul_f32 v[130:131], v[130:131], v[132:133]
	s_nop 0
	v_pk_mul_f32 v[130:131], v[130:131], v[134:135]
	v_add_f32_e32 v0, 1.0, v0
	v_cvt_pk_bf16_f32 v116, v130, v131
	v_rcp_f32_e32 v130, v0
	v_mul_f32_e32 v0, 0xbfb8aa3b, v129
	v_exp_f32_e32 v0, v0
	v_lshlrev_b32_e32 v132, 16, v221
	v_and_b32_e32 v133, 0xffff0000, v221
	v_add_f32_e32 v0, 1.0, v0
	v_rcp_f32_e32 v131, v0
	s_nop 0
	v_pk_mul_f32 v[128:129], v[128:129], v[130:131]
	s_nop 0
	v_pk_mul_f32 v[128:129], v[128:129], v[132:133]
	s_nop 0
	v_cvt_pk_bf16_f32 v117, v128, v129
	s_cbranch_vccz .LBB0_972
	s_mov_b64 s[30:31], 0

; __device__ __forceinline__ unsigned pk2(float lo, float hi) { const f32x2 v = {lo, hi}; const bf16x2_t b = __builtin_convertvector(v, bf16x2_t); return __builtin_bit_cast(unsigned, b); }
; __device__ __forceinline__ float siluf_(float x) { return x * sigmoidf_(x); }
;     template <int NA, int NM> __device__ __forceinline__ void operator()(const f32x4 (&acc)[NA][2][NM][2], const pg8::Unit& u, int ro, int wr, int wc, int fr, int fq) const {
;     ...
;                     for (int bj = 0; bj < 2; ++bj) {
;                         bf16_t* p = QV + (size_t)row * 2048 + (colt - 4096) + bj * 128;
;                         const u32x4 on = *(const u32x4*)p;
;                         u32x4 w;
;                         w.x = pk2(bflo(on.x) * siluf_(v[bj][0].x), bfhi(on.x) * siluf_(v[bj][0].y)); w.y = pk2(bflo(on.y) * siluf_(v[bj][0].z), bfhi(on.y) * siluf_(v[bj][0].w));
;                         w.z = pk2(bflo(on.z) * siluf_(v[bj][1].x), bfhi(on.z) * siluf_(v[bj][1].y)); w.w = pk2(bflo(on.w) * siluf_(v[bj][1].z), bfhi(on.w) * siluf_(v[bj][1].w));
;                         if (!dry) *(u32x4*)p = w; else asm volatile("" :: "v"(w));
.LBB0_974:
	s_nop 1
	v_add_co_u32_e32 v114, vcc, 0xfffff000, v126
	v_mul_f32_e32 v0, 0xbfb8aa3b, v124
	s_nop 0
	v_addc_co_u32_e32 v115, vcc, -1, v127, vcc
	v_exp_f32_e32 v0, v0
	s_mov_b64 s[30:31], -1
	s_and_b64 vcc, exec, s[2:3]
	v_add_f32_e32 v0, 1.0, v0
	v_rcp_f32_e32 v128, v0
	v_mul_f32_e32 v0, 0xbfb8aa3b, v125
	v_exp_f32_e32 v0, v0
	s_waitcnt vmcnt(6)
	v_lshlrev_b32_e32 v130, 16, v222
	v_add_f32_e32 v0, 1.0, v0
	v_rcp_f32_e32 v129, v0
	v_mul_f32_e32 v0, 0xbfb8aa3b, v122
	v_exp_f32_e32 v0, v0
	v_and_b32_e32 v131, 0xffff0000, v222
	v_pk_mul_f32 v[124:125], v[124:125], v[128:129]
	v_lshlrev_b32_e32 v128, 16, v223
	v_pk_mul_f32 v[124:125], v[124:125], v[130:131]
	v_add_f32_e32 v0, 1.0, v0
	v_cvt_pk_bf16_f32 v114, v124, v125
	v_rcp_f32_e32 v124, v0
	v_mul_f32_e32 v0, 0xbfb8aa3b, v123
	v_exp_f32_e32 v0, v0
	v_and_b32_e32 v129, 0xffff0000, v223
	v_add_f32_e32 v0, 1.0, v0
	v_rcp_f32_e32 v125, v0
	v_mul_f32_e32 v0, 0xbfb8aa3b, v120
	v_exp_f32_e32 v0, v0
	v_pk_mul_f32 v[122:123], v[122:123], v[124:125]
	s_nop 0
	v_pk_mul_f32 v[122:123], v[122:123], v[128:129]
	v_add_f32_e32 v0, 1.0, v0
	v_cvt_pk_bf16_f32 v115, v122, v123
	v_rcp_f32_e32 v122, v0
	v_mul_f32_e32 v0, 0xbfb8aa3b, v121
	v_exp_f32_e32 v0, v0
	v_lshlrev_b32_e32 v124, 16, v224
	v_and_b32_e32 v125, 0xffff0000, v224
	v_add_f32_e32 v0, 1.0, v0
	v_rcp_f32_e32 v123, v0
	v_mul_f32_e32 v0, 0xbfb8aa3b, v118
	v_exp_f32_e32 v0, v0
	v_pk_mul_f32 v[120:121], v[120:121], v[122:123]
	s_nop 0
	v_pk_mul_f32 v[120:121], v[120:121], v[124:125]
	v_add_f32_e32 v0, 1.0, v0
	v_cvt_pk_bf16_f32 v116, v120, v121
	v_rcp_f32_e32 v120, v0
	v_mul_f32_e32 v0, 0xbfb8aa3b, v119
	v_exp_f32_e32 v0, v0
	v_lshlrev_b32_e32 v122, 16, v225
	v_and_b32_e32 v123, 0xffff0000, v225
	v_add_f32_e32 v0, 1.0, v0
	v_rcp_f32_e32 v121, v0
	s_nop 0
	v_pk_mul_f32 v[118:119], v[118:119], v[120:121]
	s_nop 0
	v_pk_mul_f32 v[118:119], v[118:119], v[122:123]
	s_nop 0
	v_cvt_pk_bf16_f32 v117, v118, v119
	s_cbranch_vccz .LBB0_976
	s_mov_b64 s[30:31], 0
.LBB0_976:
	s_mov_b32 s100, 0x90000
	s_mov_b32 s101, 0
	v_lshl_add_u64 v[246:247], v[244:245], 0, s[100:101]
	global_load_dwordx4 v[218:221], v[246:247], off
	global_load_dwordx4 v[222:225], v[246:247], off offset:256
	s_andn2_b64 vcc, exec, s[30:31]
	s_cbranch_vccnz .LBB0_978
	s_movk_i32 s0, 0xe100
	s_mov_b32 s1, -1
	v_lshl_add_u64 v[118:119], v[126:127], 0, s[0:1]
	global_store_dwordx4 v[118:119], v[114:117], off

; __device__ __forceinline__ unsigned pk2(float lo, float hi) { const f32x2 v = {lo, hi}; const bf16x2_t b = __builtin_convertvector(v, bf16x2_t); return __builtin_bit_cast(unsigned, b); }
; __device__ __forceinline__ float siluf_(float x) { return x * sigmoidf_(x); }
;     template <int NA, int NM> __device__ __forceinline__ void operator()(const f32x4 (&acc)[NA][2][NM][2], const pg8::Unit& u, int ro, int wr, int wc, int fr, int fq) const {
;     ...
;                     for (int bj = 0; bj < 2; ++bj) {
;                         bf16_t* p = QV + (size_t)row * 2048 + (colt - 4096) + bj * 128;
;                         const u32x4 on = *(const u32x4*)p;
;                         u32x4 w;
;                         w.x = pk2(bflo(on.x) * siluf_(v[bj][0].x), bfhi(on.x) * siluf_(v[bj][0].y)); w.y = pk2(bflo(on.y) * siluf_(v[bj][0].z), bfhi(on.y) * siluf_(v[bj][0].w));
;                         w.z = pk2(bflo(on.z) * siluf_(v[bj][1].x), bfhi(on.z) * siluf_(v[bj][1].y)); w.w = pk2(bflo(on.w) * siluf_(v[bj][1].z), bfhi(on.w) * siluf_(v[bj][1].w));
;                         if (!dry) *(u32x4*)p = w; else asm volatile("" :: "v"(w));
.LBB0_984:
	s_andn2_b64 vcc, exec, s[30:31]
	s_cbranch_vccnz .LBB0_993
	v_ashrrev_i32_e32 v99, 31, v98
	v_readlane_b32 s0, v254, 19
	v_lshlrev_b64 v[98:99], 12, v[98:99]
	v_readlane_b32 s1, v254, 20
	v_mul_f32_e32 v0, 0xbfb8aa3b, v118
	v_exp_f32_e32 v0, v0
	v_lshl_add_u64 v[98:99], s[0:1], 0, v[98:99]
	v_lshl_add_u64 v[110:111], v[170:171], 1, v[98:99]
	v_add_co_u32_e32 v98, vcc, 0xffffe000, v110
	v_add_f32_e32 v0, 1.0, v0
	s_nop 0
	v_addc_co_u32_e32 v99, vcc, -1, v111, vcc
	v_rcp_f32_e32 v120, v0
	v_mul_f32_e32 v0, 0xbfb8aa3b, v119
	v_exp_f32_e32 v0, v0
	s_mov_b64 s[30:31], -1
	s_and_b64 vcc, exec, s[2:3]
	v_add_f32_e32 v0, 1.0, v0
	v_rcp_f32_e32 v121, v0
	v_mul_f32_e32 v0, 0xbfb8aa3b, v116
	v_exp_f32_e32 v0, v0
	v_pk_mul_f32 v[118:119], v[118:119], v[120:121]
	v_add_f32_e32 v0, 1.0, v0
	s_waitcnt vmcnt(7)
	v_lshlrev_b32_e32 v122, 16, v226
	v_and_b32_e32 v123, 0xffff0000, v226
	v_pk_mul_f32 v[118:119], v[118:119], v[122:123]
	v_lshlrev_b32_e32 v120, 16, v227
	v_cvt_pk_bf16_f32 v98, v118, v119
	v_rcp_f32_e32 v118, v0
	v_mul_f32_e32 v0, 0xbfb8aa3b, v117
	v_exp_f32_e32 v0, v0
	v_and_b32_e32 v121, 0xffff0000, v227
	v_add_f32_e32 v0, 1.0, v0
	v_rcp_f32_e32 v119, v0
	v_mul_f32_e32 v0, 0xbfb8aa3b, v114
	v_exp_f32_e32 v0, v0
	v_pk_mul_f32 v[116:117], v[116:117], v[118:119]
	s_nop 0
	v_pk_mul_f32 v[116:117], v[116:117], v[120:121]
	v_add_f32_e32 v0, 1.0, v0
	v_cvt_pk_bf16_f32 v99, v116, v117
	v_rcp_f32_e32 v116, v0
	v_mul_f32_e32 v0, 0xbfb8aa3b, v115
	v_exp_f32_e32 v0, v0
	v_lshlrev_b32_e32 v118, 16, v228
	v_and_b32_e32 v119, 0xffff0000, v228
	v_add_f32_e32 v0, 1.0, v0
	v_rcp_f32_e32 v117, v0
	v_mul_f32_e32 v0, 0xbfb8aa3b, v112
	v_exp_f32_e32 v0, v0
	v_pk_mul_f32 v[114:115], v[114:115], v[116:117]
	s_nop 0
	v_pk_mul_f32 v[114:115], v[114:115], v[118:119]
	v_add_f32_e32 v0, 1.0, v0
	v_cvt_pk_bf16_f32 v100, v114, v115
	v_rcp_f32_e32 v114, v0
	v_mul_f32_e32 v0, 0xbfb8aa3b, v113
	v_exp_f32_e32 v0, v0
	v_lshlrev_b32_e32 v116, 16, v229
	v_and_b32_e32 v117, 0xffff0000, v229
	v_add_f32_e32 v0, 1.0, v0
	v_rcp_f32_e32 v115, v0
	s_nop 0
	v_pk_mul_f32 v[112:113], v[112:113], v[114:115]
	s_nop 0
	v_pk_mul_f32 v[112:113], v[112:113], v[116:117]
	s_nop 0
	v_cvt_pk_bf16_f32 v101, v112, v113
	s_cbranch_vccz .LBB0_987
	s_mov_b64 s[30:31], 0

; __device__ __forceinline__ unsigned pk2(float lo, float hi) { const f32x2 v = {lo, hi}; const bf16x2_t b = __builtin_convertvector(v, bf16x2_t); return __builtin_bit_cast(unsigned, b); }
; __device__ __forceinline__ float siluf_(float x) { return x * sigmoidf_(x); }
;     template <int NA, int NM> __device__ __forceinline__ void operator()(const f32x4 (&acc)[NA][2][NM][2], const pg8::Unit& u, int ro, int wr, int wc, int fr, int fq) const {
;     ...
;                     for (int bj = 0; bj < 2; ++bj) {
;                         bf16_t* p = QV + (size_t)row * 2048 + (colt - 4096) + bj * 128;
;                         const u32x4 on = *(const u32x4*)p;
;                         u32x4 w;
;                         w.x = pk2(bflo(on.x) * siluf_(v[bj][0].x), bfhi(on.x) * siluf_(v[bj][0].y)); w.y = pk2(bflo(on.y) * siluf_(v[bj][0].z), bfhi(on.y) * siluf_(v[bj][0].w));
;                         w.z = pk2(bflo(on.z) * siluf_(v[bj][1].x), bfhi(on.z) * siluf_(v[bj][1].y)); w.w = pk2(bflo(on.w) * siluf_(v[bj][1].z), bfhi(on.w) * siluf_(v[bj][1].w));
;                         if (!dry) *(u32x4*)p = w; else asm volatile("" :: "v"(w));
.LBB0_989:
	s_nop 1
	v_add_co_u32_e32 v98, vcc, 0xfffff000, v110
	v_mul_f32_e32 v0, 0xbfb8aa3b, v108
	s_nop 0
	v_addc_co_u32_e32 v99, vcc, -1, v111, vcc
	v_exp_f32_e32 v0, v0
	s_mov_b64 s[30:31], -1
	s_and_b64 vcc, exec, s[2:3]
	v_add_f32_e32 v0, 1.0, v0
	v_rcp_f32_e32 v112, v0
	v_mul_f32_e32 v0, 0xbfb8aa3b, v109
	v_exp_f32_e32 v0, v0
	s_waitcnt vmcnt(6)
	v_lshlrev_b32_e32 v114, 16, v230
	v_add_f32_e32 v0, 1.0, v0
	v_rcp_f32_e32 v113, v0
	v_mul_f32_e32 v0, 0xbfb8aa3b, v106
	v_exp_f32_e32 v0, v0
	v_and_b32_e32 v115, 0xffff0000, v230
	v_pk_mul_f32 v[108:109], v[108:109], v[112:113]
	v_lshlrev_b32_e32 v112, 16, v231
	v_pk_mul_f32 v[108:109], v[108:109], v[114:115]
	v_add_f32_e32 v0, 1.0, v0
	v_cvt_pk_bf16_f32 v98, v108, v109
	v_rcp_f32_e32 v108, v0
	v_mul_f32_e32 v0, 0xbfb8aa3b, v107
	v_exp_f32_e32 v0, v0
	v_and_b32_e32 v113, 0xffff0000, v231
	v_add_f32_e32 v0, 1.0, v0
	v_rcp_f32_e32 v109, v0
	v_mul_f32_e32 v0, 0xbfb8aa3b, v104
	v_exp_f32_e32 v0, v0
	v_pk_mul_f32 v[106:107], v[106:107], v[108:109]
	s_nop 0
	v_pk_mul_f32 v[106:107], v[106:107], v[112:113]
	v_add_f32_e32 v0, 1.0, v0
	v_cvt_pk_bf16_f32 v99, v106, v107
	v_rcp_f32_e32 v106, v0
	v_mul_f32_e32 v0, 0xbfb8aa3b, v105
	v_exp_f32_e32 v0, v0
	v_lshlrev_b32_e32 v108, 16, v232
	v_and_b32_e32 v109, 0xffff0000, v232
	v_add_f32_e32 v0, 1.0, v0
	v_rcp_f32_e32 v107, v0
	v_mul_f32_e32 v0, 0xbfb8aa3b, v102
	v_exp_f32_e32 v0, v0
	v_pk_mul_f32 v[104:105], v[104:105], v[106:107]
	s_nop 0
	v_pk_mul_f32 v[104:105], v[104:105], v[108:109]
	v_add_f32_e32 v0, 1.0, v0
	v_cvt_pk_bf16_f32 v100, v104, v105
	v_rcp_f32_e32 v104, v0
	v_mul_f32_e32 v0, 0xbfb8aa3b, v103
	v_exp_f32_e32 v0, v0
	v_lshlrev_b32_e32 v106, 16, v233
	v_and_b32_e32 v107, 0xffff0000, v233
	v_add_f32_e32 v0, 1.0, v0
	v_rcp_f32_e32 v105, v0
	s_nop 0
	v_pk_mul_f32 v[102:103], v[102:103], v[104:105]
	s_nop 0
	v_pk_mul_f32 v[102:103], v[102:103], v[106:107]
	s_nop 0
	v_cvt_pk_bf16_f32 v101, v102, v103
	s_cbranch_vccz .LBB0_991
	s_mov_b64 s[30:31], 0
.LBB0_991:
	s_mov_b32 s100, 0xa0000
	s_mov_b32 s101, 0
	v_lshl_add_u64 v[246:247], v[244:245], 0, s[100:101]
	global_load_dwordx4 v[226:229], v[246:247], off
	global_load_dwordx4 v[230:233], v[246:247], off offset:256
	s_andn2_b64 vcc, exec, s[30:31]
	s_cbranch_vccnz .LBB0_993
	s_movk_i32 s0, 0xe100
	s_mov_b32 s1, -1
	v_lshl_add_u64 v[102:103], v[110:111], 0, s[0:1]
	global_store_dwordx4 v[102:103], v[98:101], off

; __device__ __forceinline__ unsigned pk2(float lo, float hi) { const f32x2 v = {lo, hi}; const bf16x2_t b = __builtin_convertvector(v, bf16x2_t); return __builtin_bit_cast(unsigned, b); }
; __device__ __forceinline__ float siluf_(float x) { return x * sigmoidf_(x); }
;     template <int NA, int NM> __device__ __forceinline__ void operator()(const f32x4 (&acc)[NA][2][NM][2], const pg8::Unit& u, int ro, int wr, int wc, int fr, int fq) const {
;     ...
;                     for (int bj = 0; bj < 2; ++bj) {
;                         bf16_t* p = QV + (size_t)row * 2048 + (colt - 4096) + bj * 128;
;                         const u32x4 on = *(const u32x4*)p;
;                         u32x4 w;
;                         w.x = pk2(bflo(on.x) * siluf_(v[bj][0].x), bfhi(on.x) * siluf_(v[bj][0].y)); w.y = pk2(bflo(on.y) * siluf_(v[bj][0].z), bfhi(on.y) * siluf_(v[bj][0].w));
;                         w.z = pk2(bflo(on.z) * siluf_(v[bj][1].x), bfhi(on.z) * siluf_(v[bj][1].y)); w.w = pk2(bflo(on.w) * siluf_(v[bj][1].z), bfhi(on.w) * siluf_(v[bj][1].w));
;                         if (!dry) *(u32x4*)p = w; else asm volatile("" :: "v"(w));
.LBB0_999:
	s_andn2_b64 vcc, exec, s[30:31]
	s_cbranch_vccnz .LBB0_1008
	v_ashrrev_i32_e32 v83, 31, v82
	v_readlane_b32 s0, v254, 19
	v_lshlrev_b64 v[82:83], 12, v[82:83]
	v_readlane_b32 s1, v254, 20
	v_mul_f32_e32 v0, 0xbfb8aa3b, v102
	v_exp_f32_e32 v0, v0
	v_lshl_add_u64 v[82:83], s[0:1], 0, v[82:83]
	v_lshl_add_u64 v[94:95], v[170:171], 1, v[82:83]
	v_add_co_u32_e32 v82, vcc, 0xffffe000, v94
	v_add_f32_e32 v0, 1.0, v0
	s_nop 0
	v_addc_co_u32_e32 v83, vcc, -1, v95, vcc
	v_rcp_f32_e32 v104, v0
	v_mul_f32_e32 v0, 0xbfb8aa3b, v103
	v_exp_f32_e32 v0, v0
	s_mov_b64 s[30:31], -1
	s_and_b64 vcc, exec, s[2:3]
	v_add_f32_e32 v0, 1.0, v0
	v_rcp_f32_e32 v105, v0
	v_mul_f32_e32 v0, 0xbfb8aa3b, v100
	v_exp_f32_e32 v0, v0
	v_pk_mul_f32 v[102:103], v[102:103], v[104:105]
	v_add_f32_e32 v0, 1.0, v0
	s_waitcnt vmcnt(7)
	v_lshlrev_b32_e32 v106, 16, v234
	v_and_b32_e32 v107, 0xffff0000, v234
	v_pk_mul_f32 v[102:103], v[102:103], v[106:107]
	v_lshlrev_b32_e32 v104, 16, v235
	v_cvt_pk_bf16_f32 v82, v102, v103
	v_rcp_f32_e32 v102, v0
	v_mul_f32_e32 v0, 0xbfb8aa3b, v101
	v_exp_f32_e32 v0, v0
	v_and_b32_e32 v105, 0xffff0000, v235
	v_add_f32_e32 v0, 1.0, v0
	v_rcp_f32_e32 v103, v0
	v_mul_f32_e32 v0, 0xbfb8aa3b, v98
	v_exp_f32_e32 v0, v0
	v_pk_mul_f32 v[100:101], v[100:101], v[102:103]
	s_nop 0
	v_pk_mul_f32 v[100:101], v[100:101], v[104:105]
	v_add_f32_e32 v0, 1.0, v0
	v_cvt_pk_bf16_f32 v83, v100, v101
	v_rcp_f32_e32 v100, v0
	v_mul_f32_e32 v0, 0xbfb8aa3b, v99
	v_exp_f32_e32 v0, v0
	v_lshlrev_b32_e32 v102, 16, v236
	v_and_b32_e32 v103, 0xffff0000, v236
	v_add_f32_e32 v0, 1.0, v0
	v_rcp_f32_e32 v101, v0
	v_mul_f32_e32 v0, 0xbfb8aa3b, v96
	v_exp_f32_e32 v0, v0
	v_pk_mul_f32 v[98:99], v[98:99], v[100:101]
	s_nop 0
	v_pk_mul_f32 v[98:99], v[98:99], v[102:103]
	v_add_f32_e32 v0, 1.0, v0
	v_cvt_pk_bf16_f32 v84, v98, v99
	v_rcp_f32_e32 v98, v0
	v_mul_f32_e32 v0, 0xbfb8aa3b, v97
	v_exp_f32_e32 v0, v0
	v_lshlrev_b32_e32 v100, 16, v237
	v_and_b32_e32 v101, 0xffff0000, v237
	v_add_f32_e32 v0, 1.0, v0
	v_rcp_f32_e32 v99, v0
	s_nop 0
	v_pk_mul_f32 v[96:97], v[96:97], v[98:99]
	s_nop 0
	v_pk_mul_f32 v[96:97], v[96:97], v[100:101]
	s_nop 0
	v_cvt_pk_bf16_f32 v85, v96, v97
	s_cbranch_vccz .LBB0_1002
	s_mov_b64 s[30:31], 0

; __device__ __forceinline__ unsigned pk2(float lo, float hi) { const f32x2 v = {lo, hi}; const bf16x2_t b = __builtin_convertvector(v, bf16x2_t); return __builtin_bit_cast(unsigned, b); }
; __device__ __forceinline__ float siluf_(float x) { return x * sigmoidf_(x); }
;     template <int NA, int NM> __device__ __forceinline__ void operator()(const f32x4 (&acc)[NA][2][NM][2], const pg8::Unit& u, int ro, int wr, int wc, int fr, int fq) const {
;     ...
;                     for (int bj = 0; bj < 2; ++bj) {
;                         bf16_t* p = QV + (size_t)row * 2048 + (colt - 4096) + bj * 128;
;                         const u32x4 on = *(const u32x4*)p;
;                         u32x4 w;
;                         w.x = pk2(bflo(on.x) * siluf_(v[bj][0].x), bfhi(on.x) * siluf_(v[bj][0].y)); w.y = pk2(bflo(on.y) * siluf_(v[bj][0].z), bfhi(on.y) * siluf_(v[bj][0].w));
;                         w.z = pk2(bflo(on.z) * siluf_(v[bj][1].x), bfhi(on.z) * siluf_(v[bj][1].y)); w.w = pk2(bflo(on.w) * siluf_(v[bj][1].z), bfhi(on.w) * siluf_(v[bj][1].w));
;                         if (!dry) *(u32x4*)p = w; else asm volatile("" :: "v"(w));
.LBB0_1004:
	s_nop 1
	v_add_co_u32_e32 v82, vcc, 0xfffff000, v94
	v_mul_f32_e32 v0, 0xbfb8aa3b, v92
	s_nop 0
	v_addc_co_u32_e32 v83, vcc, -1, v95, vcc
	v_exp_f32_e32 v0, v0
	s_mov_b64 s[30:31], -1
	s_and_b64 vcc, exec, s[2:3]
	v_add_f32_e32 v0, 1.0, v0
	v_rcp_f32_e32 v96, v0
	v_mul_f32_e32 v0, 0xbfb8aa3b, v93
	v_exp_f32_e32 v0, v0
	s_waitcnt vmcnt(6)
	v_lshlrev_b32_e32 v98, 16, v240
	v_add_f32_e32 v0, 1.0, v0
	v_rcp_f32_e32 v97, v0
	v_mul_f32_e32 v0, 0xbfb8aa3b, v90
	v_exp_f32_e32 v0, v0
	v_and_b32_e32 v99, 0xffff0000, v240
	v_pk_mul_f32 v[92:93], v[92:93], v[96:97]
	v_lshlrev_b32_e32 v96, 16, v241
	v_pk_mul_f32 v[92:93], v[92:93], v[98:99]
	v_add_f32_e32 v0, 1.0, v0
	v_cvt_pk_bf16_f32 v82, v92, v93
	v_rcp_f32_e32 v92, v0
	v_mul_f32_e32 v0, 0xbfb8aa3b, v91
	v_exp_f32_e32 v0, v0
	v_and_b32_e32 v97, 0xffff0000, v241
	v_add_f32_e32 v0, 1.0, v0
	v_rcp_f32_e32 v93, v0
	v_mul_f32_e32 v0, 0xbfb8aa3b, v88
	v_exp_f32_e32 v0, v0
	v_pk_mul_f32 v[90:91], v[90:91], v[92:93]
	s_nop 0
	v_pk_mul_f32 v[90:91], v[90:91], v[96:97]
	v_add_f32_e32 v0, 1.0, v0
	v_cvt_pk_bf16_f32 v83, v90, v91
	v_rcp_f32_e32 v90, v0
	v_mul_f32_e32 v0, 0xbfb8aa3b, v89
	v_exp_f32_e32 v0, v0
	v_lshlrev_b32_e32 v92, 16, v242
	v_and_b32_e32 v93, 0xffff0000, v242
	v_add_f32_e32 v0, 1.0, v0
	v_rcp_f32_e32 v91, v0
	v_mul_f32_e32 v0, 0xbfb8aa3b, v86
	v_exp_f32_e32 v0, v0
	v_pk_mul_f32 v[88:89], v[88:89], v[90:91]
	s_nop 0
	v_pk_mul_f32 v[88:89], v[88:89], v[92:93]
	v_add_f32_e32 v0, 1.0, v0
	v_cvt_pk_bf16_f32 v84, v88, v89
	v_rcp_f32_e32 v88, v0
	v_mul_f32_e32 v0, 0xbfb8aa3b, v87
	v_exp_f32_e32 v0, v0
	v_lshlrev_b32_e32 v90, 16, v243
	v_and_b32_e32 v91, 0xffff0000, v243
	v_add_f32_e32 v0, 1.0, v0
	v_rcp_f32_e32 v89, v0
	s_nop 0
	v_pk_mul_f32 v[86:87], v[86:87], v[88:89]
	s_nop 0
	v_pk_mul_f32 v[86:87], v[86:87], v[90:91]
	s_nop 0
	v_cvt_pk_bf16_f32 v85, v86, v87
	s_cbranch_vccz .LBB0_1006
	s_mov_b64 s[30:31], 0
.LBB0_1006:
	s_mov_b32 s100, 0xb0000
	s_mov_b32 s101, 0
	v_lshl_add_u64 v[246:247], v[244:245], 0, s[100:101]
	global_load_dwordx4 v[234:237], v[246:247], off
	global_load_dwordx4 v[240:243], v[246:247], off offset:256
	s_andn2_b64 vcc, exec, s[30:31]
	s_cbranch_vccnz .LBB0_1008
	s_movk_i32 s0, 0xe100
	s_mov_b32 s1, -1
	v_lshl_add_u64 v[86:87], v[94:95], 0, s[0:1]
	global_store_dwordx4 v[86:87], v[82:85], off

; __device__ __forceinline__ unsigned pk2(float lo, float hi) { const f32x2 v = {lo, hi}; const bf16x2_t b = __builtin_convertvector(v, bf16x2_t); return __builtin_bit_cast(unsigned, b); }
; __device__ __forceinline__ float siluf_(float x) { return x * sigmoidf_(x); }
;     template <int NA, int NM> __device__ __forceinline__ void operator()(const f32x4 (&acc)[NA][2][NM][2], const pg8::Unit& u, int ro, int wr, int wc, int fr, int fq) const {
;     ...
;                     for (int bj = 0; bj < 2; ++bj) {
;                         bf16_t* p = QV + (size_t)row * 2048 + (colt - 4096) + bj * 128;
;                         const u32x4 on = *(const u32x4*)p;
;                         u32x4 w;
;                         w.x = pk2(bflo(on.x) * siluf_(v[bj][0].x), bfhi(on.x) * siluf_(v[bj][0].y)); w.y = pk2(bflo(on.y) * siluf_(v[bj][0].z), bfhi(on.y) * siluf_(v[bj][0].w));
;                         w.z = pk2(bflo(on.z) * siluf_(v[bj][1].x), bfhi(on.z) * siluf_(v[bj][1].y)); w.w = pk2(bflo(on.w) * siluf_(v[bj][1].z), bfhi(on.w) * siluf_(v[bj][1].w));
;                         if (!dry) *(u32x4*)p = w; else asm volatile("" :: "v"(w));
.LBB0_1014:
	s_andn2_b64 vcc, exec, s[30:31]
	s_cbranch_vccnz .LBB0_1023
	v_ashrrev_i32_e32 v67, 31, v66
	v_readlane_b32 s0, v254, 19
	v_lshlrev_b64 v[66:67], 12, v[66:67]
	v_readlane_b32 s1, v254, 20
	v_mul_f32_e32 v0, 0xbfb8aa3b, v86
	v_exp_f32_e32 v0, v0
	v_lshl_add_u64 v[66:67], s[0:1], 0, v[66:67]
	v_lshl_add_u64 v[78:79], v[170:171], 1, v[66:67]
	v_add_co_u32_e32 v66, vcc, 0xffffe000, v78
	v_add_f32_e32 v0, 1.0, v0
	s_nop 0
	v_addc_co_u32_e32 v67, vcc, -1, v79, vcc
	v_rcp_f32_e32 v88, v0
	v_mul_f32_e32 v0, 0xbfb8aa3b, v87
	v_exp_f32_e32 v0, v0
	s_mov_b64 s[30:31], -1
	s_and_b64 vcc, exec, s[2:3]
	v_add_f32_e32 v0, 1.0, v0
	v_rcp_f32_e32 v89, v0
	v_mul_f32_e32 v0, 0xbfb8aa3b, v84
	v_exp_f32_e32 v0, v0
	v_pk_mul_f32 v[86:87], v[86:87], v[88:89]
	v_add_f32_e32 v0, 1.0, v0
	s_waitcnt vmcnt(7)
	v_lshlrev_b32_e32 v90, 16, v210
	v_and_b32_e32 v91, 0xffff0000, v210
	v_pk_mul_f32 v[86:87], v[86:87], v[90:91]
	v_lshlrev_b32_e32 v88, 16, v211
	v_cvt_pk_bf16_f32 v66, v86, v87
	v_rcp_f32_e32 v86, v0
	v_mul_f32_e32 v0, 0xbfb8aa3b, v85
	v_exp_f32_e32 v0, v0
	v_and_b32_e32 v89, 0xffff0000, v211
	v_add_f32_e32 v0, 1.0, v0
	v_rcp_f32_e32 v87, v0
	v_mul_f32_e32 v0, 0xbfb8aa3b, v82
	v_exp_f32_e32 v0, v0
	v_pk_mul_f32 v[84:85], v[84:85], v[86:87]
	s_nop 0
	v_pk_mul_f32 v[84:85], v[84:85], v[88:89]
	v_add_f32_e32 v0, 1.0, v0
	v_cvt_pk_bf16_f32 v67, v84, v85
	v_rcp_f32_e32 v84, v0
	v_mul_f32_e32 v0, 0xbfb8aa3b, v83
	v_exp_f32_e32 v0, v0
	v_lshlrev_b32_e32 v86, 16, v212
	v_and_b32_e32 v87, 0xffff0000, v212
	v_add_f32_e32 v0, 1.0, v0
	v_rcp_f32_e32 v85, v0
	v_mul_f32_e32 v0, 0xbfb8aa3b, v80
	v_exp_f32_e32 v0, v0
	v_pk_mul_f32 v[82:83], v[82:83], v[84:85]
	s_nop 0
	v_pk_mul_f32 v[82:83], v[82:83], v[86:87]
	v_add_f32_e32 v0, 1.0, v0
	v_cvt_pk_bf16_f32 v68, v82, v83
	v_rcp_f32_e32 v82, v0
	v_mul_f32_e32 v0, 0xbfb8aa3b, v81
	v_exp_f32_e32 v0, v0
	v_lshlrev_b32_e32 v84, 16, v213
	v_and_b32_e32 v85, 0xffff0000, v213
	v_add_f32_e32 v0, 1.0, v0
	v_rcp_f32_e32 v83, v0
	s_nop 0
	v_pk_mul_f32 v[80:81], v[80:81], v[82:83]
	s_nop 0
	v_pk_mul_f32 v[80:81], v[80:81], v[84:85]
	s_nop 0
	v_cvt_pk_bf16_f32 v69, v80, v81
	s_cbranch_vccz .LBB0_1017
	s_mov_b64 s[30:31], 0

; __device__ __forceinline__ unsigned pk2(float lo, float hi) { const f32x2 v = {lo, hi}; const bf16x2_t b = __builtin_convertvector(v, bf16x2_t); return __builtin_bit_cast(unsigned, b); }
; __device__ __forceinline__ float siluf_(float x) { return x * sigmoidf_(x); }
;     template <int NA, int NM> __device__ __forceinline__ void operator()(const f32x4 (&acc)[NA][2][NM][2], const pg8::Unit& u, int ro, int wr, int wc, int fr, int fq) const {
;     ...
;                     for (int bj = 0; bj < 2; ++bj) {
;                         bf16_t* p = QV + (size_t)row * 2048 + (colt - 4096) + bj * 128;
;                         const u32x4 on = *(const u32x4*)p;
;                         u32x4 w;
;                         w.x = pk2(bflo(on.x) * siluf_(v[bj][0].x), bfhi(on.x) * siluf_(v[bj][0].y)); w.y = pk2(bflo(on.y) * siluf_(v[bj][0].z), bfhi(on.y) * siluf_(v[bj][0].w));
;                         w.z = pk2(bflo(on.z) * siluf_(v[bj][1].x), bfhi(on.z) * siluf_(v[bj][1].y)); w.w = pk2(bflo(on.w) * siluf_(v[bj][1].z), bfhi(on.w) * siluf_(v[bj][1].w));
;                         if (!dry) *(u32x4*)p = w; else asm volatile("" :: "v"(w));
.LBB0_1019:
	s_nop 1
	v_add_co_u32_e32 v66, vcc, 0xfffff000, v78
	v_mul_f32_e32 v0, 0xbfb8aa3b, v76
	s_nop 0
	v_addc_co_u32_e32 v67, vcc, -1, v79, vcc
	v_exp_f32_e32 v0, v0
	s_mov_b64 s[30:31], -1
	s_and_b64 vcc, exec, s[2:3]
	v_add_f32_e32 v0, 1.0, v0
	v_rcp_f32_e32 v80, v0
	v_mul_f32_e32 v0, 0xbfb8aa3b, v77
	v_exp_f32_e32 v0, v0
	s_waitcnt vmcnt(6)
	v_lshlrev_b32_e32 v82, 16, v214
	v_add_f32_e32 v0, 1.0, v0
	v_rcp_f32_e32 v81, v0
	v_mul_f32_e32 v0, 0xbfb8aa3b, v74
	v_exp_f32_e32 v0, v0
	v_and_b32_e32 v83, 0xffff0000, v214
	v_pk_mul_f32 v[76:77], v[76:77], v[80:81]
	v_lshlrev_b32_e32 v80, 16, v215
	v_pk_mul_f32 v[76:77], v[76:77], v[82:83]
	v_add_f32_e32 v0, 1.0, v0
	v_cvt_pk_bf16_f32 v66, v76, v77
	v_rcp_f32_e32 v76, v0
	v_mul_f32_e32 v0, 0xbfb8aa3b, v75
	v_exp_f32_e32 v0, v0
	v_and_b32_e32 v81, 0xffff0000, v215
	v_add_f32_e32 v0, 1.0, v0
	v_rcp_f32_e32 v77, v0
	v_mul_f32_e32 v0, 0xbfb8aa3b, v72
	v_exp_f32_e32 v0, v0
	v_pk_mul_f32 v[74:75], v[74:75], v[76:77]
	s_nop 0
	v_pk_mul_f32 v[74:75], v[74:75], v[80:81]
	v_add_f32_e32 v0, 1.0, v0
	v_cvt_pk_bf16_f32 v67, v74, v75
	v_rcp_f32_e32 v74, v0
	v_mul_f32_e32 v0, 0xbfb8aa3b, v73
	v_exp_f32_e32 v0, v0
	v_lshlrev_b32_e32 v76, 16, v216
	v_and_b32_e32 v77, 0xffff0000, v216
	v_add_f32_e32 v0, 1.0, v0
	v_rcp_f32_e32 v75, v0
	v_mul_f32_e32 v0, 0xbfb8aa3b, v70
	v_exp_f32_e32 v0, v0
	v_pk_mul_f32 v[72:73], v[72:73], v[74:75]
	s_nop 0
	v_pk_mul_f32 v[72:73], v[72:73], v[76:77]
	v_add_f32_e32 v0, 1.0, v0
	v_cvt_pk_bf16_f32 v68, v72, v73
	v_rcp_f32_e32 v72, v0
	v_mul_f32_e32 v0, 0xbfb8aa3b, v71
	v_exp_f32_e32 v0, v0
	v_lshlrev_b32_e32 v74, 16, v217
	v_and_b32_e32 v75, 0xffff0000, v217
	v_add_f32_e32 v0, 1.0, v0
	v_rcp_f32_e32 v73, v0
	s_nop 0
	v_pk_mul_f32 v[70:71], v[70:71], v[72:73]
	s_nop 0
	v_pk_mul_f32 v[70:71], v[70:71], v[74:75]
	s_nop 0
	v_cvt_pk_bf16_f32 v69, v70, v71
	s_cbranch_vccz .LBB0_1021
	s_mov_b64 s[30:31], 0

; __device__ __forceinline__ unsigned pk2(float lo, float hi) { const f32x2 v = {lo, hi}; const bf16x2_t b = __builtin_convertvector(v, bf16x2_t); return __builtin_bit_cast(unsigned, b); }
; __device__ __forceinline__ float siluf_(float x) { return x * sigmoidf_(x); }
;     template <int NA, int NM> __device__ __forceinline__ void operator()(const f32x4 (&acc)[NA][2][NM][2], const pg8::Unit& u, int ro, int wr, int wc, int fr, int fq) const {
;     ...
;                     for (int bj = 0; bj < 2; ++bj) {
;                         bf16_t* p = QV + (size_t)row * 2048 + (colt - 4096) + bj * 128;
;                         const u32x4 on = *(const u32x4*)p;
;                         u32x4 w;
;                         w.x = pk2(bflo(on.x) * siluf_(v[bj][0].x), bfhi(on.x) * siluf_(v[bj][0].y)); w.y = pk2(bflo(on.y) * siluf_(v[bj][0].z), bfhi(on.y) * siluf_(v[bj][0].w));
;                         w.z = pk2(bflo(on.z) * siluf_(v[bj][1].x), bfhi(on.z) * siluf_(v[bj][1].y)); w.w = pk2(bflo(on.w) * siluf_(v[bj][1].z), bfhi(on.w) * siluf_(v[bj][1].w));
;                         if (!dry) *(u32x4*)p = w; else asm volatile("" :: "v"(w));
.LBB0_1029:
	s_andn2_b64 vcc, exec, s[30:31]
	s_cbranch_vccnz .LBB0_1038
	v_ashrrev_i32_e32 v51, 31, v50
	v_readlane_b32 s0, v254, 19
	v_lshlrev_b64 v[50:51], 12, v[50:51]
	v_readlane_b32 s1, v254, 20
	v_mul_f32_e32 v0, 0xbfb8aa3b, v70
	v_exp_f32_e32 v0, v0
	v_lshl_add_u64 v[50:51], s[0:1], 0, v[50:51]
	v_lshl_add_u64 v[62:63], v[170:171], 1, v[50:51]
	v_add_co_u32_e32 v50, vcc, 0xffffe000, v62
	v_add_f32_e32 v0, 1.0, v0
	s_nop 0
	v_addc_co_u32_e32 v51, vcc, -1, v63, vcc
	v_rcp_f32_e32 v72, v0
	v_mul_f32_e32 v0, 0xbfb8aa3b, v71
	v_exp_f32_e32 v0, v0
	s_mov_b64 s[30:31], -1
	s_and_b64 vcc, exec, s[2:3]
	v_add_f32_e32 v0, 1.0, v0
	v_rcp_f32_e32 v73, v0
	v_mul_f32_e32 v0, 0xbfb8aa3b, v68
	v_exp_f32_e32 v0, v0
	v_pk_mul_f32 v[70:71], v[70:71], v[72:73]
	v_add_f32_e32 v0, 1.0, v0
	s_waitcnt vmcnt(5)
	v_lshlrev_b32_e32 v74, 16, v218
	v_and_b32_e32 v75, 0xffff0000, v218
	v_pk_mul_f32 v[70:71], v[70:71], v[74:75]
	v_lshlrev_b32_e32 v72, 16, v219
	v_cvt_pk_bf16_f32 v50, v70, v71
	v_rcp_f32_e32 v70, v0
	v_mul_f32_e32 v0, 0xbfb8aa3b, v69
	v_exp_f32_e32 v0, v0
	v_and_b32_e32 v73, 0xffff0000, v219
	v_add_f32_e32 v0, 1.0, v0
	v_rcp_f32_e32 v71, v0
	v_mul_f32_e32 v0, 0xbfb8aa3b, v66
	v_exp_f32_e32 v0, v0
	v_pk_mul_f32 v[68:69], v[68:69], v[70:71]
	s_nop 0
	v_pk_mul_f32 v[68:69], v[68:69], v[72:73]
	v_add_f32_e32 v0, 1.0, v0
	v_cvt_pk_bf16_f32 v51, v68, v69
	v_rcp_f32_e32 v68, v0
	v_mul_f32_e32 v0, 0xbfb8aa3b, v67
	v_exp_f32_e32 v0, v0
	v_lshlrev_b32_e32 v70, 16, v220
	v_and_b32_e32 v71, 0xffff0000, v220
	v_add_f32_e32 v0, 1.0, v0
	v_rcp_f32_e32 v69, v0
	v_mul_f32_e32 v0, 0xbfb8aa3b, v64
	v_exp_f32_e32 v0, v0
	v_pk_mul_f32 v[66:67], v[66:67], v[68:69]
	s_nop 0
	v_pk_mul_f32 v[66:67], v[66:67], v[70:71]
	v_add_f32_e32 v0, 1.0, v0
	v_cvt_pk_bf16_f32 v52, v66, v67
	v_rcp_f32_e32 v66, v0
	v_mul_f32_e32 v0, 0xbfb8aa3b, v65
	v_exp_f32_e32 v0, v0
	v_lshlrev_b32_e32 v68, 16, v221
	v_and_b32_e32 v69, 0xffff0000, v221
	v_add_f32_e32 v0, 1.0, v0
	v_rcp_f32_e32 v67, v0
	s_nop 0
	v_pk_mul_f32 v[64:65], v[64:65], v[66:67]
	s_nop 0
	v_pk_mul_f32 v[64:65], v[64:65], v[68:69]
	s_nop 0
	v_cvt_pk_bf16_f32 v53, v64, v65
	s_cbranch_vccz .LBB0_1032
	s_mov_b64 s[30:31], 0

; __device__ __forceinline__ unsigned pk2(float lo, float hi) { const f32x2 v = {lo, hi}; const bf16x2_t b = __builtin_convertvector(v, bf16x2_t); return __builtin_bit_cast(unsigned, b); }
; __device__ __forceinline__ float siluf_(float x) { return x * sigmoidf_(x); }
;     template <int NA, int NM> __device__ __forceinline__ void operator()(const f32x4 (&acc)[NA][2][NM][2], const pg8::Unit& u, int ro, int wr, int wc, int fr, int fq) const {
;     ...
;                     for (int bj = 0; bj < 2; ++bj) {
;                         bf16_t* p = QV + (size_t)row * 2048 + (colt - 4096) + bj * 128;
;                         const u32x4 on = *(const u32x4*)p;
;                         u32x4 w;
;                         w.x = pk2(bflo(on.x) * siluf_(v[bj][0].x), bfhi(on.x) * siluf_(v[bj][0].y)); w.y = pk2(bflo(on.y) * siluf_(v[bj][0].z), bfhi(on.y) * siluf_(v[bj][0].w));
;                         w.z = pk2(bflo(on.z) * siluf_(v[bj][1].x), bfhi(on.z) * siluf_(v[bj][1].y)); w.w = pk2(bflo(on.w) * siluf_(v[bj][1].z), bfhi(on.w) * siluf_(v[bj][1].w));
;                         if (!dry) *(u32x4*)p = w; else asm volatile("" :: "v"(w));
.LBB0_1034:
	s_nop 1
	v_add_co_u32_e32 v50, vcc, 0xfffff000, v62
	v_mul_f32_e32 v0, 0xbfb8aa3b, v60
	s_nop 0
	v_addc_co_u32_e32 v51, vcc, -1, v63, vcc
	v_exp_f32_e32 v0, v0
	s_mov_b64 s[30:31], -1
	s_and_b64 vcc, exec, s[2:3]
	v_add_f32_e32 v0, 1.0, v0
	v_rcp_f32_e32 v64, v0
	v_mul_f32_e32 v0, 0xbfb8aa3b, v61
	v_exp_f32_e32 v0, v0
	s_waitcnt vmcnt(4)
	v_lshlrev_b32_e32 v66, 16, v222
	v_add_f32_e32 v0, 1.0, v0
	v_rcp_f32_e32 v65, v0
	v_mul_f32_e32 v0, 0xbfb8aa3b, v58
	v_exp_f32_e32 v0, v0
	v_and_b32_e32 v67, 0xffff0000, v222
	v_pk_mul_f32 v[60:61], v[60:61], v[64:65]
	v_lshlrev_b32_e32 v64, 16, v223
	v_pk_mul_f32 v[60:61], v[60:61], v[66:67]
	v_add_f32_e32 v0, 1.0, v0
	v_cvt_pk_bf16_f32 v50, v60, v61
	v_rcp_f32_e32 v60, v0
	v_mul_f32_e32 v0, 0xbfb8aa3b, v59
	v_exp_f32_e32 v0, v0
	v_and_b32_e32 v65, 0xffff0000, v223
	v_add_f32_e32 v0, 1.0, v0
	v_rcp_f32_e32 v61, v0
	v_mul_f32_e32 v0, 0xbfb8aa3b, v56
	v_exp_f32_e32 v0, v0
	v_pk_mul_f32 v[58:59], v[58:59], v[60:61]
	s_nop 0
	v_pk_mul_f32 v[58:59], v[58:59], v[64:65]
	v_add_f32_e32 v0, 1.0, v0
	v_cvt_pk_bf16_f32 v51, v58, v59
	v_rcp_f32_e32 v58, v0
	v_mul_f32_e32 v0, 0xbfb8aa3b, v57
	v_exp_f32_e32 v0, v0
	v_lshlrev_b32_e32 v60, 16, v224
	v_and_b32_e32 v61, 0xffff0000, v224
	v_add_f32_e32 v0, 1.0, v0
	v_rcp_f32_e32 v59, v0
	v_mul_f32_e32 v0, 0xbfb8aa3b, v54
	v_exp_f32_e32 v0, v0
	v_pk_mul_f32 v[56:57], v[56:57], v[58:59]
	s_nop 0
	v_pk_mul_f32 v[56:57], v[56:57], v[60:61]
	v_add_f32_e32 v0, 1.0, v0
	v_cvt_pk_bf16_f32 v52, v56, v57
	v_rcp_f32_e32 v56, v0
	v_mul_f32_e32 v0, 0xbfb8aa3b, v55
	v_exp_f32_e32 v0, v0
	v_lshlrev_b32_e32 v58, 16, v225
	v_and_b32_e32 v59, 0xffff0000, v225
	v_add_f32_e32 v0, 1.0, v0
	v_rcp_f32_e32 v57, v0
	s_nop 0
	v_pk_mul_f32 v[54:55], v[54:55], v[56:57]
	s_nop 0
	v_pk_mul_f32 v[54:55], v[54:55], v[58:59]
	s_nop 0
	v_cvt_pk_bf16_f32 v53, v54, v55
	s_cbranch_vccz .LBB0_1036
	s_mov_b64 s[30:31], 0

; __device__ __forceinline__ unsigned pk2(float lo, float hi) { const f32x2 v = {lo, hi}; const bf16x2_t b = __builtin_convertvector(v, bf16x2_t); return __builtin_bit_cast(unsigned, b); }
; __device__ __forceinline__ float siluf_(float x) { return x * sigmoidf_(x); }
;     template <int NA, int NM> __device__ __forceinline__ void operator()(const f32x4 (&acc)[NA][2][NM][2], const pg8::Unit& u, int ro, int wr, int wc, int fr, int fq) const {
;     ...
;                     for (int bj = 0; bj < 2; ++bj) {
;                         bf16_t* p = QV + (size_t)row * 2048 + (colt - 4096) + bj * 128;
;                         const u32x4 on = *(const u32x4*)p;
;                         u32x4 w;
;                         w.x = pk2(bflo(on.x) * siluf_(v[bj][0].x), bfhi(on.x) * siluf_(v[bj][0].y)); w.y = pk2(bflo(on.y) * siluf_(v[bj][0].z), bfhi(on.y) * siluf_(v[bj][0].w));
;                         w.z = pk2(bflo(on.z) * siluf_(v[bj][1].x), bfhi(on.z) * siluf_(v[bj][1].y)); w.w = pk2(bflo(on.w) * siluf_(v[bj][1].z), bfhi(on.w) * siluf_(v[bj][1].w));
;                         if (!dry) *(u32x4*)p = w; else asm volatile("" :: "v"(w));
.LBB0_1044:
	s_andn2_b64 vcc, exec, s[30:31]
	s_cbranch_vccnz .LBB0_1053
	v_ashrrev_i32_e32 v35, 31, v34
	v_readlane_b32 s0, v254, 19
	v_lshlrev_b64 v[34:35], 12, v[34:35]
	v_readlane_b32 s1, v254, 20
	v_mul_f32_e32 v0, 0xbfb8aa3b, v54
	v_exp_f32_e32 v0, v0
	v_lshl_add_u64 v[34:35], s[0:1], 0, v[34:35]
	v_lshl_add_u64 v[46:47], v[170:171], 1, v[34:35]
	v_add_co_u32_e32 v34, vcc, 0xffffe000, v46
	v_add_f32_e32 v0, 1.0, v0
	s_nop 0
	v_addc_co_u32_e32 v35, vcc, -1, v47, vcc
	v_rcp_f32_e32 v56, v0
	v_mul_f32_e32 v0, 0xbfb8aa3b, v55
	v_exp_f32_e32 v0, v0
	s_mov_b64 s[30:31], -1
	s_and_b64 vcc, exec, s[2:3]
	v_add_f32_e32 v0, 1.0, v0
	v_rcp_f32_e32 v57, v0
	v_mul_f32_e32 v0, 0xbfb8aa3b, v52
	v_exp_f32_e32 v0, v0
	v_pk_mul_f32 v[54:55], v[54:55], v[56:57]
	v_add_f32_e32 v0, 1.0, v0
	s_waitcnt vmcnt(3)
	v_lshlrev_b32_e32 v58, 16, v226
	v_and_b32_e32 v59, 0xffff0000, v226
	v_pk_mul_f32 v[54:55], v[54:55], v[58:59]
	v_lshlrev_b32_e32 v56, 16, v227
	v_cvt_pk_bf16_f32 v34, v54, v55
	v_rcp_f32_e32 v54, v0
	v_mul_f32_e32 v0, 0xbfb8aa3b, v53
	v_exp_f32_e32 v0, v0
	v_and_b32_e32 v57, 0xffff0000, v227
	v_add_f32_e32 v0, 1.0, v0
	v_rcp_f32_e32 v55, v0
	v_mul_f32_e32 v0, 0xbfb8aa3b, v50
	v_exp_f32_e32 v0, v0
	v_pk_mul_f32 v[52:53], v[52:53], v[54:55]
	s_nop 0
	v_pk_mul_f32 v[52:53], v[52:53], v[56:57]
	v_add_f32_e32 v0, 1.0, v0
	v_cvt_pk_bf16_f32 v35, v52, v53
	v_rcp_f32_e32 v52, v0
	v_mul_f32_e32 v0, 0xbfb8aa3b, v51
	v_exp_f32_e32 v0, v0
	v_lshlrev_b32_e32 v54, 16, v228
	v_and_b32_e32 v55, 0xffff0000, v228
	v_add_f32_e32 v0, 1.0, v0
	v_rcp_f32_e32 v53, v0
	v_mul_f32_e32 v0, 0xbfb8aa3b, v48
	v_exp_f32_e32 v0, v0
	v_pk_mul_f32 v[50:51], v[50:51], v[52:53]
	s_nop 0
	v_pk_mul_f32 v[50:51], v[50:51], v[54:55]
	v_add_f32_e32 v0, 1.0, v0
	v_cvt_pk_bf16_f32 v36, v50, v51
	v_rcp_f32_e32 v50, v0
	v_mul_f32_e32 v0, 0xbfb8aa3b, v49
	v_exp_f32_e32 v0, v0
	v_lshlrev_b32_e32 v52, 16, v229
	v_and_b32_e32 v53, 0xffff0000, v229
	v_add_f32_e32 v0, 1.0, v0
	v_rcp_f32_e32 v51, v0
	s_nop 0
	v_pk_mul_f32 v[48:49], v[48:49], v[50:51]
	s_nop 0
	v_pk_mul_f32 v[48:49], v[48:49], v[52:53]
	s_nop 0
	v_cvt_pk_bf16_f32 v37, v48, v49
	s_cbranch_vccz .LBB0_1047
	s_mov_b64 s[30:31], 0

; __device__ __forceinline__ unsigned pk2(float lo, float hi) { const f32x2 v = {lo, hi}; const bf16x2_t b = __builtin_convertvector(v, bf16x2_t); return __builtin_bit_cast(unsigned, b); }
; __device__ __forceinline__ float siluf_(float x) { return x * sigmoidf_(x); }
;     template <int NA, int NM> __device__ __forceinline__ void operator()(const f32x4 (&acc)[NA][2][NM][2], const pg8::Unit& u, int ro, int wr, int wc, int fr, int fq) const {
;     ...
;                     for (int bj = 0; bj < 2; ++bj) {
;                         bf16_t* p = QV + (size_t)row * 2048 + (colt - 4096) + bj * 128;
;                         const u32x4 on = *(const u32x4*)p;
;                         u32x4 w;
;                         w.x = pk2(bflo(on.x) * siluf_(v[bj][0].x), bfhi(on.x) * siluf_(v[bj][0].y)); w.y = pk2(bflo(on.y) * siluf_(v[bj][0].z), bfhi(on.y) * siluf_(v[bj][0].w));
;                         w.z = pk2(bflo(on.z) * siluf_(v[bj][1].x), bfhi(on.z) * siluf_(v[bj][1].y)); w.w = pk2(bflo(on.w) * siluf_(v[bj][1].z), bfhi(on.w) * siluf_(v[bj][1].w));
;                         if (!dry) *(u32x4*)p = w; else asm volatile("" :: "v"(w));
.LBB0_1049:
	s_nop 1
	v_add_co_u32_e32 v34, vcc, 0xfffff000, v46
	v_mul_f32_e32 v0, 0xbfb8aa3b, v44
	s_nop 0
	v_addc_co_u32_e32 v35, vcc, -1, v47, vcc
	v_exp_f32_e32 v0, v0
	s_mov_b64 s[30:31], -1
	s_and_b64 vcc, exec, s[2:3]
	v_add_f32_e32 v0, 1.0, v0
	v_rcp_f32_e32 v48, v0
	v_mul_f32_e32 v0, 0xbfb8aa3b, v45
	v_exp_f32_e32 v0, v0
	s_waitcnt vmcnt(2)
	v_lshlrev_b32_e32 v50, 16, v230
	v_add_f32_e32 v0, 1.0, v0
	v_rcp_f32_e32 v49, v0
	v_mul_f32_e32 v0, 0xbfb8aa3b, v42
	v_exp_f32_e32 v0, v0
	v_and_b32_e32 v51, 0xffff0000, v230
	v_pk_mul_f32 v[44:45], v[44:45], v[48:49]
	v_lshlrev_b32_e32 v48, 16, v231
	v_pk_mul_f32 v[44:45], v[44:45], v[50:51]
	v_add_f32_e32 v0, 1.0, v0
	v_cvt_pk_bf16_f32 v34, v44, v45
	v_rcp_f32_e32 v44, v0
	v_mul_f32_e32 v0, 0xbfb8aa3b, v43
	v_exp_f32_e32 v0, v0
	v_and_b32_e32 v49, 0xffff0000, v231
	v_add_f32_e32 v0, 1.0, v0
	v_rcp_f32_e32 v45, v0
	v_mul_f32_e32 v0, 0xbfb8aa3b, v40
	v_exp_f32_e32 v0, v0
	v_pk_mul_f32 v[42:43], v[42:43], v[44:45]
	s_nop 0
	v_pk_mul_f32 v[42:43], v[42:43], v[48:49]
	v_add_f32_e32 v0, 1.0, v0
	v_cvt_pk_bf16_f32 v35, v42, v43
	v_rcp_f32_e32 v42, v0
	v_mul_f32_e32 v0, 0xbfb8aa3b, v41
	v_exp_f32_e32 v0, v0
	v_lshlrev_b32_e32 v44, 16, v232
	v_and_b32_e32 v45, 0xffff0000, v232
	v_add_f32_e32 v0, 1.0, v0
	v_rcp_f32_e32 v43, v0
	v_mul_f32_e32 v0, 0xbfb8aa3b, v38
	v_exp_f32_e32 v0, v0
	v_pk_mul_f32 v[40:41], v[40:41], v[42:43]
	s_nop 0
	v_pk_mul_f32 v[40:41], v[40:41], v[44:45]
	v_add_f32_e32 v0, 1.0, v0
	v_cvt_pk_bf16_f32 v36, v40, v41
	v_rcp_f32_e32 v40, v0
	v_mul_f32_e32 v0, 0xbfb8aa3b, v39
	v_exp_f32_e32 v0, v0
	v_lshlrev_b32_e32 v42, 16, v233
	v_and_b32_e32 v43, 0xffff0000, v233
	v_add_f32_e32 v0, 1.0, v0
	v_rcp_f32_e32 v41, v0
	s_nop 0
	v_pk_mul_f32 v[38:39], v[38:39], v[40:41]
	s_nop 0
	v_pk_mul_f32 v[38:39], v[38:39], v[42:43]
	s_nop 0
	v_cvt_pk_bf16_f32 v37, v38, v39
	s_cbranch_vccz .LBB0_1051
	s_mov_b64 s[30:31], 0

; __device__ __forceinline__ unsigned pk2(float lo, float hi) { const f32x2 v = {lo, hi}; const bf16x2_t b = __builtin_convertvector(v, bf16x2_t); return __builtin_bit_cast(unsigned, b); }
; __device__ __forceinline__ float siluf_(float x) { return x * sigmoidf_(x); }
;     template <int NA, int NM> __device__ __forceinline__ void operator()(const f32x4 (&acc)[NA][2][NM][2], const pg8::Unit& u, int ro, int wr, int wc, int fr, int fq) const {
;     ...
;                     for (int bj = 0; bj < 2; ++bj) {
;                         bf16_t* p = QV + (size_t)row * 2048 + (colt - 4096) + bj * 128;
;                         const u32x4 on = *(const u32x4*)p;
;                         u32x4 w;
;                         w.x = pk2(bflo(on.x) * siluf_(v[bj][0].x), bfhi(on.x) * siluf_(v[bj][0].y)); w.y = pk2(bflo(on.y) * siluf_(v[bj][0].z), bfhi(on.y) * siluf_(v[bj][0].w));
;                         w.z = pk2(bflo(on.z) * siluf_(v[bj][1].x), bfhi(on.z) * siluf_(v[bj][1].y)); w.w = pk2(bflo(on.w) * siluf_(v[bj][1].z), bfhi(on.w) * siluf_(v[bj][1].w));
;                         if (!dry) *(u32x4*)p = w; else asm volatile("" :: "v"(w));
.LBB0_1059:
	s_andn2_b64 vcc, exec, s[30:31]
	s_cbranch_vccnz .LBB0_1068
	v_ashrrev_i32_e32 v3, 31, v2
	v_readlane_b32 s0, v254, 19
	v_lshlrev_b64 v[2:3], 12, v[2:3]
	v_readlane_b32 s1, v254, 20
	v_mul_f32_e32 v0, 0xbfb8aa3b, v30
	v_exp_f32_e32 v0, v0
	v_lshl_add_u64 v[2:3], s[0:1], 0, v[2:3]
	v_lshl_add_u64 v[14:15], v[170:171], 1, v[2:3]
	v_add_co_u32_e32 v2, vcc, 0xffffe000, v14
	v_add_f32_e32 v0, 1.0, v0
	s_nop 0
	v_addc_co_u32_e32 v3, vcc, -1, v15, vcc
	v_rcp_f32_e32 v18, v0
	v_mul_f32_e32 v0, 0xbfb8aa3b, v31
	v_exp_f32_e32 v0, v0
	s_mov_b64 s[30:31], -1
	s_and_b64 vcc, exec, s[2:3]
	v_add_f32_e32 v0, 1.0, v0
	v_rcp_f32_e32 v19, v0
	v_mul_f32_e32 v0, 0xbfb8aa3b, v32
	v_exp_f32_e32 v0, v0
	v_pk_mul_f32 v[18:19], v[30:31], v[18:19]
	v_add_f32_e32 v0, 1.0, v0
	s_waitcnt vmcnt(1)
	v_lshlrev_b32_e32 v20, 16, v234
	v_and_b32_e32 v21, 0xffff0000, v234
	v_pk_mul_f32 v[18:19], v[18:19], v[20:21]
	v_lshlrev_b32_e32 v20, 16, v235
	v_cvt_pk_bf16_f32 v2, v18, v19
	v_rcp_f32_e32 v18, v0
	v_mul_f32_e32 v0, 0xbfb8aa3b, v33
	v_exp_f32_e32 v0, v0
	v_and_b32_e32 v21, 0xffff0000, v235
	v_add_f32_e32 v0, 1.0, v0
	v_rcp_f32_e32 v19, v0
	v_mul_f32_e32 v0, 0xbfb8aa3b, v22
	v_exp_f32_e32 v0, v0
	v_pk_mul_f32 v[18:19], v[32:33], v[18:19]
	s_nop 0
	v_pk_mul_f32 v[18:19], v[18:19], v[20:21]
	v_add_f32_e32 v0, 1.0, v0
	v_cvt_pk_bf16_f32 v3, v18, v19
	v_rcp_f32_e32 v18, v0
	v_mul_f32_e32 v0, 0xbfb8aa3b, v23
	v_exp_f32_e32 v0, v0
	v_lshlrev_b32_e32 v20, 16, v236
	v_and_b32_e32 v21, 0xffff0000, v236
	v_add_f32_e32 v0, 1.0, v0
	v_rcp_f32_e32 v19, v0
	v_mul_f32_e32 v0, 0xbfb8aa3b, v16
	v_exp_f32_e32 v0, v0
	v_pk_mul_f32 v[18:19], v[22:23], v[18:19]
	s_nop 0
	v_pk_mul_f32 v[18:19], v[18:19], v[20:21]
	v_add_f32_e32 v0, 1.0, v0
	v_cvt_pk_bf16_f32 v4, v18, v19
	v_rcp_f32_e32 v18, v0
	v_mul_f32_e32 v0, 0xbfb8aa3b, v17
	v_exp_f32_e32 v0, v0
	v_lshlrev_b32_e32 v20, 16, v237
	v_and_b32_e32 v21, 0xffff0000, v237
	v_add_f32_e32 v0, 1.0, v0
	v_rcp_f32_e32 v19, v0
	s_nop 0
	v_pk_mul_f32 v[16:17], v[16:17], v[18:19]
	s_nop 0
	v_pk_mul_f32 v[16:17], v[16:17], v[20:21]
	s_nop 0
	v_cvt_pk_bf16_f32 v5, v16, v17
	s_cbranch_vccz .LBB0_1062
	s_mov_b64 s[30:31], 0

; __device__ __forceinline__ unsigned pk2(float lo, float hi) { const f32x2 v = {lo, hi}; const bf16x2_t b = __builtin_convertvector(v, bf16x2_t); return __builtin_bit_cast(unsigned, b); }
; __device__ __forceinline__ float siluf_(float x) { return x * sigmoidf_(x); }
;     template <int NA, int NM> __device__ __forceinline__ void operator()(const f32x4 (&acc)[NA][2][NM][2], const pg8::Unit& u, int ro, int wr, int wc, int fr, int fq) const {
;     ...
;                     for (int bj = 0; bj < 2; ++bj) {
;                         bf16_t* p = QV + (size_t)row * 2048 + (colt - 4096) + bj * 128;
;                         const u32x4 on = *(const u32x4*)p;
;                         u32x4 w;
;                         w.x = pk2(bflo(on.x) * siluf_(v[bj][0].x), bfhi(on.x) * siluf_(v[bj][0].y)); w.y = pk2(bflo(on.y) * siluf_(v[bj][0].z), bfhi(on.y) * siluf_(v[bj][0].w));
;                         w.z = pk2(bflo(on.z) * siluf_(v[bj][1].x), bfhi(on.z) * siluf_(v[bj][1].y)); w.w = pk2(bflo(on.w) * siluf_(v[bj][1].z), bfhi(on.w) * siluf_(v[bj][1].w));
;                         if (!dry) *(u32x4*)p = w; else asm volatile("" :: "v"(w));
.LBB0_1064:
	s_nop 1
	v_add_co_u32_e32 v2, vcc, 0xfffff000, v14
	v_mul_f32_e32 v0, 0xbfb8aa3b, v12
	s_nop 0
	v_addc_co_u32_e32 v3, vcc, -1, v15, vcc
	v_exp_f32_e32 v0, v0
	s_mov_b64 s[30:31], -1
	s_and_b64 vcc, exec, s[2:3]
	v_add_f32_e32 v0, 1.0, v0
	v_rcp_f32_e32 v16, v0
	v_mul_f32_e32 v0, 0xbfb8aa3b, v13
	v_exp_f32_e32 v0, v0
	s_waitcnt vmcnt(0)
	v_lshlrev_b32_e32 v18, 16, v240
	v_add_f32_e32 v0, 1.0, v0
	v_rcp_f32_e32 v17, v0
	v_mul_f32_e32 v0, 0xbfb8aa3b, v10
	v_exp_f32_e32 v0, v0
	v_and_b32_e32 v19, 0xffff0000, v240
	v_pk_mul_f32 v[12:13], v[12:13], v[16:17]
	v_lshlrev_b32_e32 v16, 16, v241
	v_pk_mul_f32 v[12:13], v[12:13], v[18:19]
	v_add_f32_e32 v0, 1.0, v0
	v_cvt_pk_bf16_f32 v2, v12, v13
	v_rcp_f32_e32 v12, v0
	v_mul_f32_e32 v0, 0xbfb8aa3b, v11
	v_exp_f32_e32 v0, v0
	v_and_b32_e32 v17, 0xffff0000, v241
	v_add_f32_e32 v0, 1.0, v0
	v_rcp_f32_e32 v13, v0
	v_mul_f32_e32 v0, 0xbfb8aa3b, v8
	v_exp_f32_e32 v0, v0
	v_pk_mul_f32 v[10:11], v[10:11], v[12:13]
	s_nop 0
	v_pk_mul_f32 v[10:11], v[10:11], v[16:17]
	v_add_f32_e32 v0, 1.0, v0
	v_cvt_pk_bf16_f32 v3, v10, v11
	v_rcp_f32_e32 v10, v0
	v_mul_f32_e32 v0, 0xbfb8aa3b, v9
	v_exp_f32_e32 v0, v0
	v_lshlrev_b32_e32 v12, 16, v242
	v_and_b32_e32 v13, 0xffff0000, v242
	v_add_f32_e32 v0, 1.0, v0
	v_rcp_f32_e32 v11, v0
	v_mul_f32_e32 v0, 0xbfb8aa3b, v6
	v_exp_f32_e32 v0, v0
	v_pk_mul_f32 v[8:9], v[8:9], v[10:11]
	s_nop 0
	v_pk_mul_f32 v[8:9], v[8:9], v[12:13]
	v_add_f32_e32 v0, 1.0, v0
	v_cvt_pk_bf16_f32 v4, v8, v9
	v_rcp_f32_e32 v8, v0
	v_mul_f32_e32 v0, 0xbfb8aa3b, v7
	v_exp_f32_e32 v0, v0
	v_lshlrev_b32_e32 v10, 16, v243
	v_and_b32_e32 v11, 0xffff0000, v243
	v_add_f32_e32 v0, 1.0, v0
	v_rcp_f32_e32 v9, v0
	s_nop 0
	v_pk_mul_f32 v[6:7], v[6:7], v[8:9]
	s_nop 0
	v_pk_mul_f32 v[6:7], v[6:7], v[10:11]
	s_nop 0
	v_cvt_pk_bf16_f32 v5, v6, v7
	s_cbranch_vccz .LBB0_1066
	s_mov_b64 s[30:31], 0

; __attribute__((amdgpu_num_vgpr(VGPR_CAP)))
; __global__ void __launch_bounds__(NTHR, 2) dit_fwd(Args args) {
	.amdhsa_kernel _Z7dit_fwd4Args
		.amdhsa_group_segment_fixed_size 0
		.amdhsa_private_segment_fixed_size 0
		.amdhsa_kernarg_size 472
		.amdhsa_user_sgpr_count 2
		.amdhsa_user_sgpr_dispatch_ptr 0
		.amdhsa_user_sgpr_queue_ptr 0
		.amdhsa_user_sgpr_kernarg_segment_ptr 1
		.amdhsa_user_sgpr_dispatch_id 0
		.amdhsa_user_sgpr_kernarg_preload_length 0
		.amdhsa_user_sgpr_kernarg_preload_offset 0
		.amdhsa_user_sgpr_private_segment_size 0
		.amdhsa_uses_dynamic_stack 0
		.amdhsa_enable_private_segment 0
		.amdhsa_system_sgpr_workgroup_id_x 1
		.amdhsa_system_sgpr_workgroup_id_y 0
		.amdhsa_system_sgpr_workgroup_id_z 0
		.amdhsa_system_sgpr_workgroup_info 0
		.amdhsa_system_vgpr_workitem_id 0
		.amdhsa_next_free_vgpr 256
		.amdhsa_next_free_sgpr 102
		.amdhsa_accum_offset 256
		.amdhsa_reserve_vcc 1
		.amdhsa_float_round_mode_32 0
		.amdhsa_float_round_mode_16_64 0
		.amdhsa_float_denorm_mode_32 3
		.amdhsa_float_denorm_mode_16_64 3
		.amdhsa_dx10_clamp 1
		.amdhsa_ieee_mode 1
		.amdhsa_fp16_overflow 0
		.amdhsa_tg_split 0
		.amdhsa_exception_fp_ieee_invalid_op 0
		.amdhsa_exception_fp_denorm_src 0
		.amdhsa_exception_fp_ieee_div_zero 0
		.amdhsa_exception_fp_ieee_overflow 0
		.amdhsa_exception_fp_ieee_underflow 0
		.amdhsa_exception_fp_ieee_inexact 0
		.amdhsa_exception_int_div_zero 0
	.end_amdhsa_kernel

; __attribute__((amdgpu_num_vgpr(VGPR_CAP)))
; __global__ void __launch_bounds__(NTHR, 2) dit_fwd(Args args) {
amdhsa.kernels:
  - .agpr_count:     0
    .args:
      - .offset:         0
        .size:           216
        .value_kind:     by_value
      - .offset:         216
        .size:           4
        .value_kind:     hidden_block_count_x
      - .offset:         220
        .size:           4
        .value_kind:     hidden_block_count_y
      - .offset:         224
        .size:           4
        .value_kind:     hidden_block_count_z
      - .offset:         228
        .size:           2
        .value_kind:     hidden_group_size_x
      - .offset:         230
        .size:           2
        .value_kind:     hidden_group_size_y
      - .offset:         232
        .size:           2
        .value_kind:     hidden_group_size_z
      - .offset:         234
        .size:           2
        .value_kind:     hidden_remainder_x
      - .offset:         236
        .size:           2
        .value_kind:     hidden_remainder_y
      - .offset:         238
        .size:           2
        .value_kind:     hidden_remainder_z
      - .offset:         256
        .size:           8
        .value_kind:     hidden_global_offset_x
      - .offset:         264
        .size:           8
        .value_kind:     hidden_global_offset_y
      - .offset:         272
        .size:           8
        .value_kind:     hidden_global_offset_z
      - .offset:         280
        .size:           2
        .value_kind:     hidden_grid_dims
      - .offset:         336
        .size:           4
        .value_kind:     hidden_dynamic_lds_size
    .group_segment_fixed_size: 0
    .kernarg_segment_align: 8
    .kernarg_segment_size: 472
    .language:       OpenCL C
    .language_version:
      - 2
      - 0
    .max_flat_workgroup_size: 512
    .name:           _Z7dit_fwd4Args
    .private_segment_fixed_size: 0
    .sgpr_count:     108
    .sgpr_spill_count: 582
    .symbol:         _Z7dit_fwd4Args.kd
    .uniform_work_group_size: 1
    .uses_dynamic_stack: false
    .vgpr_count:     256
    .vgpr_spill_count: 0
    .wavefront_size: 64
